# stack9 plus write-through sc0 sc1 on the H (rmsnorm output) dwordx2 stores of EW1, EW2 and ew_init
# speedup vs baseline: 1.0097x; 1.0097x over previous
; __device__ __forceinline__ void ew_post(const bf16* Y, const float* xin, float* xout, const float* gpost, const float* gnext, bf16* H, int gw, int ngw, int lane) {
;     for (int m0 = EW_NR * gw; m0 < NTOK; m0 += EW_NR * ngw) {
;         f32x4 y[EW_NR][4], xv[EW_NR][4]; float s[EW_NR];
; #pragma unroll
;         for (int q = 0; q < EW_NR; ++q) { const v2u* yr = (const v2u*)(Y + (size_t)(m0 + q) * DM) + lane; const f32x4* xr = (const f32x4*)(xin + (size_t)(m0 + q) * DM) + lane;
; #pragma unroll
;             for (int j = 0; j < 4; ++j) { const v2u w = __builtin_nontemporal_load(yr + 64 * j); y[q][j] = (f32x4){bf_lo(w.x), bf_hi(w.x), bf_lo(w.y), bf_hi(w.y)}; xv[q][j] = __builtin_nontemporal_load(xr + 64 * j); } }
; #pragma unroll
;         for (int q = 0; q < EW_NR; ++q) { s[q] = 0.f;
; #pragma unroll
;             for (int j = 0; j < 4; ++j) s[q] += (y[q][j].x * y[q][j].x + y[q][j].y * y[q][j].y) + (y[q][j].z * y[q][j].z + y[q][j].w * y[q][j].w); }
.LBB0_191:
	global_load_dwordx2 v[16:17], v[68:69], off offset:-4096 nt
	global_load_dwordx2 v[18:19], v[68:69], off offset:-2048 nt
	global_load_dwordx2 v[20:21], v[68:69], off nt
	v_add_co_u32_e32 v0, vcc, 0xfffff000, v68
	s_movk_i32 s4, 0xf000
	s_nop 0
	v_addc_co_u32_e32 v1, vcc, -1, v69, vcc
	global_load_dwordx2 v[22:23], v[0:1], off offset:-2048 nt
	global_load_dwordx2 v[24:25], v[0:1], off offset:-3584 nt
	global_load_dwordx2 v[26:27], v[0:1], off offset:-3072 nt
	global_load_dwordx2 v[28:29], v[0:1], off offset:-2560 nt
	global_load_dwordx2 v[30:31], v[0:1], off offset:-1536 nt
	global_load_dwordx2 v[42:43], v[68:69], off offset:-3584 nt
	global_load_dwordx2 v[84:85], v[68:69], off offset:-3072 nt
	global_load_dwordx2 v[94:95], v[68:69], off offset:-2560 nt
	global_load_dwordx4 v[4:7], v[70:71], off offset:-3072 nt
	global_load_dwordx2 v[38:39], v[0:1], off offset:-1024 nt
	global_load_dwordx2 v[46:47], v[68:69], off offset:-1536 nt
	global_load_dwordx2 v[86:87], v[68:69], off offset:-1024 nt
	global_load_dwordx2 v[88:89], v[68:69], off offset:-512 nt
	global_load_dwordx2 v[40:41], v[0:1], off offset:-512 nt
	v_add_co_u32_e32 v36, vcc, s4, v70
	s_movk_i32 s6, 0xe000
	s_nop 0
	v_addc_co_u32_e32 v37, vcc, -1, v71, vcc
	v_add_co_u32_e32 v48, vcc, 0xffffd000, v70
	s_mov_b64 s[4:5], vcc
	v_addc_co_u32_e64 v49, s[4:5], -1, v71, s[4:5]
	global_load_dwordx4 v[0:3], v[48:49], off offset:-3072 nt
	v_add_co_u32_e32 v50, vcc, s6, v70
	global_load_dwordx4 v[8:11], v[36:37], off offset:-3072 nt
	s_nop 0
	v_addc_co_u32_e32 v51, vcc, -1, v71, vcc
	global_load_dwordx4 v[12:15], v[50:51], off offset:-3072 nt
	global_load_dwordx4 v[124:127], v[48:49], off offset:-2048 nt
	global_load_dwordx4 v[128:131], v[50:51], off offset:-2048 nt
	global_load_dwordx4 v[132:135], v[36:37], off offset:-2048 nt
	global_load_dwordx4 v[136:139], v[70:71], off offset:-2048 nt
	global_load_dwordx4 v[140:143], v[48:49], off offset:-1024 nt
	global_load_dwordx4 v[144:147], v[50:51], off offset:-1024 nt
	global_load_dwordx4 v[148:151], v[36:37], off offset:-1024 nt
	global_load_dwordx4 v[152:155], v[70:71], off offset:-1024 nt
	global_load_dwordx4 v[156:159], v[48:49], off nt
	global_load_dwordx4 v[160:163], v[70:71], off offset:-4096 nt
	global_load_dwordx4 v[164:167], v[50:51], off nt
	global_load_dwordx4 v[168:171], v[70:71], off nt
	s_waitcnt vmcnt(0)
	v_lshlrev_b32_e32 v79, 16, v22
	v_and_b32_e32 v59, 0xffff0000, v22
	v_lshlrev_b32_e32 v60, 16, v23
	v_and_b32_e32 v61, 0xffff0000, v23
	v_lshlrev_b32_e32 v54, 16, v17
	v_and_b32_e32 v55, 0xffff0000, v17
	v_lshlrev_b32_e32 v72, 16, v19
	v_and_b32_e32 v73, 0xffff0000, v19
	v_and_b32_e32 v17, 0xffff0000, v24
	v_and_b32_e32 v19, 0xffff0000, v25
	v_lshlrev_b32_e32 v83, 16, v16
	v_and_b32_e32 v53, 0xffff0000, v16
	v_lshlrev_b32_e32 v81, 16, v18
	v_and_b32_e32 v63, 0xffff0000, v18
	v_lshlrev_b32_e32 v16, 16, v24
	v_lshlrev_b32_e32 v18, 16, v25
	v_and_b32_e32 v23, 0xffff0000, v27
	v_and_b32_e32 v22, 0xffff0000, v26
	v_lshlrev_b32_e32 v32, 16, v28
	v_and_b32_e32 v33, 0xffff0000, v28
	v_mul_f32_e32 v24, v19, v19
	v_mul_f32_e32 v28, v17, v17
	v_mov_b32_e32 v25, v79
	v_lshlrev_b32_e32 v77, 16, v20
	v_and_b32_e32 v57, 0xffff0000, v20
	v_lshlrev_b32_e32 v74, 16, v21
	v_and_b32_e32 v75, 0xffff0000, v21
	v_lshlrev_b32_e32 v21, 16, v27
	v_lshlrev_b32_e32 v20, 16, v26
	v_lshlrev_b32_e32 v34, 16, v29
	v_and_b32_e32 v35, 0xffff0000, v29
	v_pk_mul_f32 v[26:27], v[22:23], v[22:23]
	v_pk_fma_f32 v[90:91], v[18:19], v[18:19], v[24:25] op_sel_hi:[1,1,0]
	v_pk_fma_f32 v[28:29], v[16:17], v[16:17], v[28:29] op_sel_hi:[1,1,0]
	v_mul_f32_e32 v44, v33, v33
	v_mul_f32_e32 v52, v35, v35
	v_pk_fma_f32 v[26:27], v[20:21], v[20:21], v[26:27]
	v_mov_b32_e32 v78, v28
	v_mov_b32_e32 v24, v90
	v_mul_f32_e32 v56, v59, v59
	v_mul_f32_e32 v58, v60, v60
	v_mul_f32_e32 v62, v61, v61
	v_pk_fma_f32 v[44:45], v[32:33], v[32:33], v[44:45] op_sel_hi:[1,1,0]
	v_pk_fma_f32 v[92:93], v[34:35], v[34:35], v[52:53] op_sel_hi:[1,1,0]
	v_pk_add_f32 v[28:29], v[28:29], v[90:91]
	v_pk_add_f32 v[26:27], v[26:27], v[26:27] op_sel:[0,1] op_sel_hi:[1,0]
	v_pk_mul_f32 v[24:25], v[78:79], v[24:25]
	v_mov_b32_e32 v45, v58
	v_mov_b32_e32 v27, v56
	v_mov_b32_e32 v29, v25
	v_mov_b32_e32 v93, v62
	v_pk_add_f32 v[24:25], v[28:29], v[26:27]
	v_pk_add_f32 v[26:27], v[44:45], v[92:93]
	v_and_b32_e32 v45, 0xffff0000, v30
	v_and_b32_e32 v93, 0xffff0000, v31
	v_pk_add_f32 v[102:103], v[24:25], v[26:27]
	v_lshlrev_b32_e32 v44, 16, v30
	v_lshlrev_b32_e32 v92, 16, v31
	v_mul_f32_e32 v24, v93, v93
	v_and_b32_e32 v27, 0xffff0000, v39
	v_and_b32_e32 v26, 0xffff0000, v38
	v_mul_f32_e32 v52, v45, v45
	v_pk_fma_f32 v[28:29], v[92:93], v[92:93], v[24:25] op_sel_hi:[1,1,0]
	v_lshlrev_b32_e32 v25, 16, v39
	v_lshlrev_b32_e32 v24, 16, v38
	v_pk_mul_f32 v[30:31], v[26:27], v[26:27]
	v_pk_fma_f32 v[90:91], v[44:45], v[44:45], v[52:53] op_sel_hi:[1,1,0]
	v_pk_fma_f32 v[30:31], v[24:25], v[24:25], v[30:31]
	v_mov_b32_e32 v82, v90
	v_mov_b32_e32 v96, v28
	v_mov_b32_e32 v97, v83
	v_mul_f32_e32 v56, v53, v53
	v_pk_add_f32 v[28:29], v[90:91], v[28:29]
	v_pk_mul_f32 v[90:91], v[82:83], v[96:97]
	v_pk_add_f32 v[30:31], v[30:31], v[30:31] op_sel:[0,1] op_sel_hi:[1,0]
	v_lshlrev_b32_e32 v38, 16, v40
	v_and_b32_e32 v39, 0xffff0000, v40
	v_lshlrev_b32_e32 v40, 16, v41
	v_and_b32_e32 v41, 0xffff0000, v41
	v_mov_b32_e32 v29, v91
	v_mov_b32_e32 v31, v56
	v_pk_add_f32 v[28:29], v[28:29], v[30:31]
	v_mul_f32_e32 v30, v39, v39
	v_mul_f32_e32 v52, v41, v41
	v_mul_f32_e32 v58, v54, v54
	v_mul_f32_e32 v62, v55, v55
	v_pk_fma_f32 v[30:31], v[38:39], v[38:39], v[30:31] op_sel_hi:[1,1,0]
	v_pk_fma_f32 v[90:91], v[40:41], v[40:41], v[52:53] op_sel_hi:[1,1,0]
; __device__ __forceinline__ void ew_post(const bf16* Y, const float* xin, float* xout, const float* gpost, const float* gnext, bf16* H, int gw, int ngw, int lane) {
;     ...
;         for (int q = 0; q < EW_NR; ++q) { s[q] = 0.f;
; #pragma unroll
;             for (int j = 0; j < 4; ++j) s[q] += (y[q][j].x * y[q][j].x + y[q][j].y * y[q][j].y) + (y[q][j].z * y[q][j].z + y[q][j].w * y[q][j].w); }
;         float rstd[EW_NR], s2[EW_NR];
; #pragma unroll
;         for (int q = 0; q < EW_NR; ++q) { rstd[q] = rsqrtf(wave_sum(s[q]) * (1.f / DM) + RMS_EPS); s2[q] = 0.f; }
	v_mov_b32_e32 v31, v58
	v_mov_b32_e32 v91, v62
	v_pk_add_f32 v[30:31], v[30:31], v[90:91]
	v_and_b32_e32 v97, 0xffff0000, v43
	v_pk_add_f32 v[114:115], v[28:29], v[30:31]
	v_and_b32_e32 v91, 0xffff0000, v42
	v_lshlrev_b32_e32 v96, 16, v43
	v_mul_f32_e32 v28, v97, v97
	v_and_b32_e32 v31, 0xffff0000, v85
	v_and_b32_e32 v30, 0xffff0000, v84
	v_lshlrev_b32_e32 v90, 16, v42
	v_pk_fma_f32 v[98:99], v[96:97], v[96:97], v[28:29] op_sel_hi:[1,1,0]
	v_lshlrev_b32_e32 v29, 16, v85
	v_lshlrev_b32_e32 v28, 16, v84
	v_pk_mul_f32 v[42:43], v[30:31], v[30:31]
	v_mul_f32_e32 v52, v91, v91
	v_pk_fma_f32 v[100:101], v[28:29], v[28:29], v[42:43]
	v_lshlrev_b32_e32 v42, 16, v94
	v_and_b32_e32 v43, 0xffff0000, v94
	v_lshlrev_b32_e32 v84, 16, v95
	v_and_b32_e32 v85, 0xffff0000, v95
	v_pk_fma_f32 v[94:95], v[90:91], v[90:91], v[52:53] op_sel_hi:[1,1,0]
	v_mov_b32_e32 v110, v98
	v_mov_b32_e32 v80, v94
	v_mov_b32_e32 v111, v81
	v_pk_add_f32 v[94:95], v[94:95], v[98:99]
	v_pk_mul_f32 v[98:99], v[80:81], v[110:111]
	s_nop 1
	v_mov_b32_e32 v110, v192
	v_mov_b32_e32 v111, v193
	v_mov_b32_e32 v112, v194
	v_mov_b32_e32 v113, v195
	v_mul_f32_e32 v56, v63, v63
	v_mov_b32_e32 v95, v99
	v_pk_add_f32 v[98:99], v[100:101], v[100:101] op_sel:[0,1] op_sel_hi:[1,0]
	v_mul_f32_e32 v52, v43, v43
	v_mov_b32_e32 v99, v56
	v_pk_add_f32 v[94:95], v[94:95], v[98:99]
	v_pk_fma_f32 v[98:99], v[42:43], v[42:43], v[52:53] op_sel_hi:[1,1,0]
	v_mul_f32_e32 v52, v85, v85
	v_mul_f32_e32 v58, v72, v72
	v_mul_f32_e32 v62, v73, v73
	v_pk_fma_f32 v[100:101], v[84:85], v[84:85], v[52:53] op_sel_hi:[1,1,0]
	v_mov_b32_e32 v99, v58
	v_mov_b32_e32 v101, v62
	v_pk_add_f32 v[98:99], v[98:99], v[100:101]
	v_and_b32_e32 v101, 0xffff0000, v47
	v_pk_add_f32 v[116:117], v[94:95], v[98:99]
	v_and_b32_e32 v99, 0xffff0000, v46
	v_lshlrev_b32_e32 v98, 16, v46
	v_lshlrev_b32_e32 v100, 16, v47
	v_mul_f32_e32 v46, v101, v101
	v_mul_f32_e32 v52, v99, v99
	v_pk_fma_f32 v[118:119], v[100:101], v[100:101], v[46:47] op_sel_hi:[1,1,0]
	v_pk_fma_f32 v[122:123], v[98:99], v[98:99], v[52:53] op_sel_hi:[1,1,0]
	v_and_b32_e32 v95, 0xffff0000, v87
	v_mov_b32_e32 v76, v122
	v_pk_add_f32 v[122:123], v[122:123], v[118:119]
	v_mov_b32_e32 v119, v77
	v_pk_mul_f32 v[118:119], v[76:77], v[118:119]
	v_and_b32_e32 v94, 0xffff0000, v86
	v_mov_b32_e32 v123, v119
	v_mov_b32_e32 v118, v114
	v_mov_b32_e32 v119, v102
	v_mov_b32_e32 v102, v115
	v_pk_add_f32 v[102:103], v[118:119], v[102:103]
	ds_bpermute_b32 v115, v104, v103
	ds_bpermute_b32 v114, v104, v102
	v_lshlrev_b32_e32 v47, 16, v87
	v_lshlrev_b32_e32 v46, 16, v86
	v_pk_mul_f32 v[86:87], v[94:95], v[94:95]
	v_mul_f32_e32 v56, v57, v57
	v_pk_fma_f32 v[120:121], v[46:47], v[46:47], v[86:87]
	v_and_b32_e32 v87, 0xffff0000, v88
	s_waitcnt lgkmcnt(0)
	v_pk_add_f32 v[102:103], v[102:103], v[114:115]
	v_lshlrev_b32_e32 v86, 16, v88
	v_lshlrev_b32_e32 v88, 16, v89
	v_and_b32_e32 v89, 0xffff0000, v89
	v_pk_add_f32 v[118:119], v[120:121], v[120:121] op_sel:[0,1] op_sel_hi:[1,0]
	ds_bpermute_b32 v115, v105, v103
	ds_bpermute_b32 v114, v105, v102
	v_mul_f32_e32 v52, v87, v87
	v_mov_b32_e32 v119, v56
	v_pk_fma_f32 v[120:121], v[86:87], v[86:87], v[52:53] op_sel_hi:[1,1,0]
	v_mul_f32_e32 v52, v89, v89
	v_mul_f32_e32 v58, v74, v74
	v_mul_f32_e32 v62, v75, v75
	v_pk_add_f32 v[118:119], v[122:123], v[118:119]
	v_pk_fma_f32 v[122:123], v[88:89], v[88:89], v[52:53] op_sel_hi:[1,1,0]
	v_mov_b32_e32 v121, v58
	v_mov_b32_e32 v123, v62
	v_pk_add_f32 v[120:121], v[120:121], v[122:123]
	s_waitcnt lgkmcnt(0)
	v_pk_add_f32 v[102:103], v[102:103], v[114:115]
	v_pk_add_f32 v[118:119], v[118:119], v[120:121]
	ds_bpermute_b32 v115, v106, v103
	ds_bpermute_b32 v114, v106, v102
	v_mov_b32_e32 v120, v118
	v_mov_b32_e32 v121, v116
	v_mov_b32_e32 v116, v119
	v_pk_add_f32 v[116:117], v[120:121], v[116:117]
	ds_bpermute_b32 v119, v104, v117
	ds_bpermute_b32 v118, v104, v116
	s_waitcnt lgkmcnt(2)
	v_pk_add_f32 v[102:103], v[102:103], v[114:115]
	ds_bpermute_b32 v115, v107, v103
	ds_bpermute_b32 v114, v107, v102
	v_mov_b32_e32 v62, v81
	s_waitcnt lgkmcnt(2)
	v_pk_add_f32 v[118:119], v[116:117], v[118:119]
	ds_bpermute_b32 v121, v105, v119
	ds_bpermute_b32 v120, v105, v118
	s_waitcnt lgkmcnt(2)
	v_pk_add_f32 v[102:103], v[102:103], v[114:115]
	ds_bpermute_b32 v115, v108, v103
	ds_bpermute_b32 v114, v108, v102
	s_waitcnt lgkmcnt(2)
	v_pk_add_f32 v[118:119], v[118:119], v[120:121]
	ds_bpermute_b32 v121, v106, v119
	ds_bpermute_b32 v120, v106, v118
	s_waitcnt lgkmcnt(2)
	v_pk_add_f32 v[102:103], v[102:103], v[114:115]
	ds_bpermute_b32 v123, v109, v103
	ds_bpermute_b32 v122, v109, v102
	s_nop 1
	v_mov_b32_e32 v114, v124
	v_mov_b32_e32 v115, v125
	v_mov_b32_e32 v116, v126
	v_mov_b32_e32 v117, v127
	s_waitcnt lgkmcnt(2)
	v_pk_add_f32 v[118:119], v[118:119], v[120:121]
	ds_bpermute_b32 v121, v107, v119
	ds_bpermute_b32 v120, v107, v118
	s_waitcnt lgkmcnt(2)
	v_pk_add_f32 v[102:103], v[102:103], v[122:123]
	v_mov_b64_e32 v[122:123], s[24:25]
	v_pk_fma_f32 v[102:103], v[102:103], s[44:45], v[122:123] op_sel_hi:[1,0,0]
	s_waitcnt lgkmcnt(0)
	v_pk_add_f32 v[118:119], v[118:119], v[120:121]
	v_mul_f32_e32 v52, 0x4b800000, v103
	v_cmp_gt_f32_e32 vcc, s3, v103
	ds_bpermute_b32 v121, v108, v119
	ds_bpermute_b32 v120, v108, v118
	v_cndmask_b32_e32 v52, v103, v52, vcc
	v_rsq_f32_e32 v52, v52
	v_mul_f32_e32 v56, 0x4b800000, v102
	v_cmp_gt_f32_e64 s[4:5], s3, v102
	v_mul_f32_e32 v58, 0x45800000, v52
	s_nop 0
	v_cndmask_b32_e64 v56, v102, v56, s[4:5]
	s_waitcnt lgkmcnt(0)
; __device__ __forceinline__ void ew_post(const bf16* Y, const float* xin, float* xout, const float* gpost, const float* gnext, bf16* H, int gw, int ngw, int lane) {
;     ...
; #pragma unroll
;         for (int j = 0; j < 4; ++j) { const f32x4 g = *((const f32x4*)gpost + lane + 64 * j);
; #pragma unroll
;             for (int q = 0; q < EW_NR; ++q) { xv[q][j] = xv[q][j] + y[q][j] * rstd[q] * g; __builtin_nontemporal_store(xv[q][j], (f32x4*)(xout + (size_t)(m0 + q) * DM) + lane + 64 * j);
;                 s2[q] += (xv[q][j].x * xv[q][j].x + xv[q][j].y * xv[q][j].y) + (xv[q][j].z * xv[q][j].z + xv[q][j].w * xv[q][j].w); } }
	v_pk_add_f32 v[102:103], v[118:119], v[120:121]
	v_cndmask_b32_e32 v76, v52, v58, vcc
	v_rsq_f32_e32 v52, v56
	ds_bpermute_b32 v119, v109, v103
	ds_bpermute_b32 v118, v109, v102
	v_pk_mul_f32 v[16:17], v[76:77], v[16:17] op_sel_hi:[0,1]
	v_pk_fma_f32 v[0:1], v[16:17], v[110:111], v[0:1]
	v_mul_f32_e32 v16, 0x45800000, v52
	v_cndmask_b32_e64 v78, v52, v16, s[4:5]
	s_waitcnt lgkmcnt(0)
	v_pk_add_f32 v[16:17], v[102:103], v[118:119]
	v_pk_mul_f32 v[18:19], v[76:77], v[18:19] op_sel_hi:[0,1]
	v_pk_fma_f32 v[16:17], v[16:17], s[44:45], v[122:123] op_sel_hi:[1,0,0]
	v_pk_fma_f32 v[2:3], v[18:19], v[112:113], v[2:3]
	v_mul_f32_e32 v18, 0x4b800000, v17
	v_cmp_gt_f32_e32 vcc, s3, v17
	s_nop 1
	v_mov_b32_e32 v118, v128
	v_mov_b32_e32 v119, v129
	v_mov_b32_e32 v120, v130
	v_mov_b32_e32 v121, v131
	v_pk_mul_f32 v[34:35], v[76:77], v[34:35] op_sel_hi:[0,1]
	v_cndmask_b32_e32 v17, v17, v18, vcc
	v_rsq_f32_e32 v17, v17
	v_pk_mul_f32 v[18:19], v[78:79], v[44:45] op_sel_hi:[0,1]
	v_pk_fma_f32 v[12:13], v[18:19], v[110:111], v[12:13]
	v_pk_mul_f32 v[44:45], v[78:79], v[92:93] op_sel_hi:[0,1]
	v_mul_f32_e32 v18, 0x45800000, v17
	v_cndmask_b32_e32 v80, v17, v18, vcc
	v_mul_f32_e32 v17, 0x4b800000, v16
	v_cmp_gt_f32_e32 vcc, s3, v16
	v_pk_fma_f32 v[14:15], v[44:45], v[112:113], v[14:15]
	v_pk_mul_f32 v[18:19], v[80:81], v[96:97] op_sel_hi:[0,1]
	v_cndmask_b32_e32 v16, v16, v17, vcc
	v_rsq_f32_e32 v44, v16
	v_pk_mul_f32 v[16:17], v[80:81], v[90:91] op_sel_hi:[0,1]
	s_nop 1
	v_mov_b32_e32 v90, v132
	v_mov_b32_e32 v91, v133
	v_mov_b32_e32 v92, v134
	v_mov_b32_e32 v93, v135
	v_pk_fma_f32 v[16:17], v[110:111], v[16:17], v[8:9]
	v_mul_f32_e32 v8, 0x45800000, v44
	v_cndmask_b32_e32 v82, v44, v8, vcc
	v_pk_fma_f32 v[18:19], v[112:113], v[18:19], v[10:11]
	v_pk_mul_f32 v[8:9], v[82:83], v[98:99] op_sel_hi:[0,1]
	v_pk_mul_f32 v[10:11], v[82:83], v[100:101] op_sel_hi:[0,1]
	global_store_dwordx4 v[48:49], v[0:3], off offset:-3072 sc0 sc1 nt
	global_store_dwordx4 v[50:51], v[12:15], off offset:-3072 sc0 sc1 nt
	global_store_dwordx4 v[36:37], v[16:19], off offset:-3072 sc0 sc1 nt
	v_pk_fma_f32 v[6:7], v[112:113], v[10:11], v[6:7]
	v_pk_fma_f32 v[4:5], v[110:111], v[8:9], v[4:5]
	s_nop 1
	v_mov_b32_e32 v96, v136
	v_mov_b32_e32 v97, v137
	v_mov_b32_e32 v98, v138
	v_mov_b32_e32 v99, v139
	v_mov_b32_e32 v8, v21
	global_store_dwordx4 v[70:71], v[4:7], off offset:-3072 sc0 sc1 nt
	s_nop 1
	v_mov_b32_e32 v100, v196
	v_mov_b32_e32 v101, v197
	v_mov_b32_e32 v102, v198
	v_mov_b32_e32 v103, v199
	s_nop 1
	v_mov_b32_e32 v110, v140
	v_mov_b32_e32 v111, v141
	v_mov_b32_e32 v112, v142
	v_mov_b32_e32 v113, v143
	v_mov_b32_e32 v9, v23
	v_mov_b32_e32 v21, v22
	v_pk_mul_f32 v[10:11], v[76:77], v[8:9] op_sel_hi:[0,1]
	v_pk_mul_f32 v[8:9], v[76:77], v[20:21] op_sel_hi:[0,1]
	v_mov_b32_e32 v20, v25
	v_mov_b32_e32 v21, v27
	v_mov_b32_e32 v25, v26
	v_pk_mul_f32 v[22:23], v[78:79], v[20:21] op_sel_hi:[0,1]
	v_pk_mul_f32 v[20:21], v[78:79], v[24:25] op_sel_hi:[0,1]
	v_mov_b32_e32 v24, v29
	v_mov_b32_e32 v25, v31
	v_mov_b32_e32 v29, v30
	v_pk_mul_f32 v[26:27], v[80:81], v[24:25] op_sel_hi:[0,1]
	v_pk_mul_f32 v[24:25], v[80:81], v[28:29] op_sel_hi:[0,1]
	v_mov_b32_e32 v28, v47
	v_mov_b32_e32 v29, v95
	v_mov_b32_e32 v47, v94
	v_pk_mul_f32 v[30:31], v[82:83], v[28:29] op_sel_hi:[0,1]
	v_pk_mul_f32 v[28:29], v[82:83], v[46:47] op_sel_hi:[0,1]
	v_pk_mul_f32 v[32:33], v[76:77], v[32:33] op_sel_hi:[0,1]
	v_pk_mul_f32 v[40:41], v[78:79], v[40:41] op_sel_hi:[0,1]
	v_pk_mul_f32 v[38:39], v[78:79], v[38:39] op_sel_hi:[0,1]
	v_mov_b32_e32 v56, v77
	v_mov_b32_e32 v58, v79
	v_mov_b32_e32 v52, v83
	v_pk_mul_f32 v[74:75], v[82:83], v[74:75] op_sel_hi:[0,1]
	v_pk_mul_f32 v[58:59], v[76:77], v[58:59] op_sel_hi:[0,1]
	v_pk_mul_f32 v[72:73], v[80:81], v[72:73] op_sel_hi:[0,1]
	v_pk_mul_f32 v[54:55], v[78:79], v[54:55] op_sel_hi:[0,1]
	v_pk_mul_f32 v[52:53], v[78:79], v[52:53] op_sel_hi:[0,1]
	s_andn2_b64 vcc, exec, s[20:21]
	v_pk_fma_f32 v[8:9], v[8:9], v[100:101], v[114:115]
	v_pk_fma_f32 v[10:11], v[10:11], v[102:103], v[116:117]
	v_pk_fma_f32 v[20:21], v[20:21], v[100:101], v[118:119]
	v_pk_fma_f32 v[22:23], v[22:23], v[102:103], v[120:121]
	v_pk_fma_f32 v[24:25], v[100:101], v[24:25], v[90:91]
	v_pk_fma_f32 v[26:27], v[102:103], v[26:27], v[92:93]
	v_pk_fma_f32 v[28:29], v[100:101], v[28:29], v[96:97]
	v_pk_fma_f32 v[30:31], v[102:103], v[30:31], v[98:99]
	global_store_dwordx4 v[48:49], v[8:11], off offset:-2048 sc0 sc1 nt
	global_store_dwordx4 v[50:51], v[20:23], off offset:-2048 sc0 sc1 nt
	global_store_dwordx4 v[36:37], v[24:27], off offset:-2048 sc0 sc1 nt
	global_store_dwordx4 v[70:71], v[28:31], off offset:-2048 sc0 sc1 nt
	s_nop 1
	v_mov_b32_e32 v90, v200
	v_mov_b32_e32 v91, v201
	v_mov_b32_e32 v92, v202
	v_mov_b32_e32 v93, v203
	s_nop 1
	v_mov_b32_e32 v44, v144
	v_mov_b32_e32 v45, v145
	v_mov_b32_e32 v46, v146
	v_mov_b32_e32 v47, v147
	s_nop 1
	v_mov_b32_e32 v94, v148
	v_mov_b32_e32 v95, v149
	v_mov_b32_e32 v96, v150
	v_mov_b32_e32 v97, v151
	s_nop 1
	v_mov_b32_e32 v98, v152
	v_mov_b32_e32 v99, v153
	v_mov_b32_e32 v100, v154
	v_mov_b32_e32 v101, v155
	s_nop 1
	v_mov_b32_e32 v114, v156
	v_mov_b32_e32 v115, v157
	v_mov_b32_e32 v116, v158
	v_mov_b32_e32 v117, v159
	s_nop 1
	v_mov_b32_e32 v118, v160
	v_mov_b32_e32 v119, v161
	v_mov_b32_e32 v120, v162
	v_mov_b32_e32 v121, v163
	v_pk_fma_f32 v[32:33], v[32:33], v[90:91], v[110:111]
	v_pk_fma_f32 v[34:35], v[34:35], v[92:93], v[112:113]
	v_pk_fma_f32 v[44:45], v[38:39], v[90:91], v[44:45]
	v_pk_fma_f32 v[46:47], v[40:41], v[92:93], v[46:47]
	v_pk_mul_f32 v[38:39], v[80:81], v[84:85] op_sel_hi:[0,1]
	v_pk_mul_f32 v[40:41], v[80:81], v[42:43] op_sel_hi:[0,1]
; __device__ __forceinline__ void ew_post(const bf16* Y, const float* xin, float* xout, const float* gpost, const float* gnext, bf16* H, int gw, int ngw, int lane) {
;     ...
;         for (int j = 0; j < 4; ++j) { const f32x4 g = *((const f32x4*)gpost + lane + 64 * j);
; #pragma unroll
;             for (int q = 0; q < EW_NR; ++q) { xv[q][j] = xv[q][j] + y[q][j] * rstd[q] * g; __builtin_nontemporal_store(xv[q][j], (f32x4*)(xout + (size_t)(m0 + q) * DM) + lane + 64 * j);
;                 s2[q] += (xv[q][j].x * xv[q][j].x + xv[q][j].y * xv[q][j].y) + (xv[q][j].z * xv[q][j].z + xv[q][j].w * xv[q][j].w); } }
;         if (gnext) {
;             float r2[EW_NR];
; #pragma unroll
;             for (int q = 0; q < EW_NR; ++q) r2[q] = rsqrtf(wave_sum(s2[q]) * (1.f / DM) + RMS_EPS);
	s_nop 1
	v_mov_b32_e32 v110, v164
	v_mov_b32_e32 v111, v165
	v_mov_b32_e32 v112, v166
	v_mov_b32_e32 v113, v167
	v_pk_fma_f32 v[40:41], v[40:41], v[90:91], v[94:95]
	v_pk_fma_f32 v[42:43], v[38:39], v[92:93], v[96:97]
	global_store_dwordx4 v[48:49], v[32:35], off offset:-1024 sc0 sc1 nt
	global_store_dwordx4 v[50:51], v[44:47], off offset:-1024 sc0 sc1 nt
	global_store_dwordx4 v[36:37], v[40:43], off offset:-1024 sc0 sc1 nt
	v_pk_mul_f32 v[38:39], v[82:83], v[88:89] op_sel_hi:[0,1]
	v_pk_mul_f32 v[36:37], v[82:83], v[86:87] op_sel_hi:[0,1]
	v_pk_fma_f32 v[36:37], v[90:91], v[36:37], v[98:99]
	v_pk_fma_f32 v[38:39], v[92:93], v[38:39], v[100:101]
	global_store_dwordx4 v[70:71], v[36:39], off offset:-1024 sc0 sc1 nt
	s_nop 1
	v_mov_b32_e32 v88, v204
	v_mov_b32_e32 v89, v205
	v_mov_b32_e32 v90, v206
	v_mov_b32_e32 v91, v207
	s_nop 1
	v_mov_b32_e32 v84, v168
	v_mov_b32_e32 v85, v169
	v_mov_b32_e32 v86, v170
	v_mov_b32_e32 v87, v171
	v_pk_mul_f32 v[82:83], v[82:83], v[56:57] op_sel_hi:[0,1]
	v_pk_mul_f32 v[56:57], v[76:77], v[60:61] op_sel_hi:[0,1]
	v_pk_mul_f32 v[80:81], v[80:81], v[62:63] op_sel_hi:[0,1]
	v_pk_fma_f32 v[60:61], v[58:59], v[88:89], v[114:115]
	v_pk_fma_f32 v[62:63], v[56:57], v[90:91], v[116:117]
	v_pk_fma_f32 v[56:57], v[52:53], v[88:89], v[110:111]
	v_pk_fma_f32 v[58:59], v[54:55], v[90:91], v[112:113]
	v_pk_fma_f32 v[52:53], v[80:81], v[88:89], v[118:119]
	v_pk_fma_f32 v[54:55], v[72:73], v[90:91], v[120:121]
	global_store_dwordx4 v[48:49], v[60:63], off sc0 sc1 nt
	global_store_dwordx4 v[50:51], v[56:59], off sc0 sc1 nt
	global_store_dwordx4 v[70:71], v[52:55], off offset:-4096 sc0 sc1 nt
	v_pk_fma_f32 v[48:49], v[82:83], v[88:89], v[84:85]
	v_pk_fma_f32 v[50:51], v[74:75], v[90:91], v[86:87]
	global_store_dwordx4 v[70:71], v[48:51], off sc0 sc1 nt
	s_cbranch_vccnz .LBB0_190
	v_pk_mul_f32 v[72:73], v[6:7], v[6:7]
	v_pk_mul_f32 v[74:75], v[4:5], v[4:5]
	v_mul_f32_e32 v80, v49, v49
	v_pk_mov_b32 v[76:77], v[74:75], v[72:73] op_sel:[1,0]
	v_mov_b32_e32 v75, v73
	v_pk_add_f32 v[72:73], v[76:77], v[74:75]
	v_pk_mul_f32 v[74:75], v[30:31], v[30:31]
	v_pk_mul_f32 v[76:77], v[28:29], v[28:29]
	v_mul_f32_e32 v81, v50, v50
	v_pk_mov_b32 v[78:79], v[76:77], v[74:75] op_sel:[1,0]
	v_mov_b32_e32 v77, v75
	v_pk_add_f32 v[74:75], v[78:79], v[76:77]
	v_mul_f32_e32 v76, v37, v37
	v_mul_f32_e32 v78, v48, v48
	v_pk_fma_f32 v[76:77], v[36:37], v[36:37], v[76:77] op_sel_hi:[1,1,0]
	v_mul_f32_e32 v82, v51, v51
	v_mov_b32_e32 v77, v78
	v_mul_f32_e32 v78, v39, v39
	v_pk_fma_f32 v[78:79], v[38:39], v[38:39], v[78:79] op_sel_hi:[1,1,0]
	v_pk_add_f32 v[72:73], v[72:73], v[72:73] op_sel:[0,1] op_sel_hi:[1,0]
	v_pk_add_f32 v[74:75], v[74:75], v[74:75] op_sel:[0,1] op_sel_hi:[1,0]
	v_mov_b32_e32 v79, v80
	v_mov_b32_e32 v73, v81
	v_mov_b32_e32 v75, v82
	v_pk_add_f32 v[76:77], v[76:77], v[78:79]
	v_pk_add_f32 v[72:73], v[72:73], v[74:75]
	v_pk_mul_f32 v[74:75], v[16:17], v[16:17]
	v_pk_add_f32 v[76:77], v[76:77], v[72:73]
	v_pk_mul_f32 v[72:73], v[18:19], v[18:19]
	v_mul_f32_e32 v88, v53, v53
	v_pk_mov_b32 v[78:79], v[74:75], v[72:73] op_sel:[1,0]
	v_mov_b32_e32 v75, v73
	v_pk_add_f32 v[72:73], v[78:79], v[74:75]
	v_pk_mul_f32 v[74:75], v[26:27], v[26:27]
	v_pk_mul_f32 v[78:79], v[24:25], v[24:25]
	v_mul_f32_e32 v89, v54, v54
	v_pk_mov_b32 v[80:81], v[78:79], v[74:75] op_sel:[1,0]
	v_mov_b32_e32 v79, v75
	v_pk_add_f32 v[74:75], v[80:81], v[78:79]
	v_mul_f32_e32 v80, v52, v52
	v_pk_add_f32 v[78:79], v[72:73], v[72:73] op_sel:[0,1] op_sel_hi:[1,0]
	v_pk_mul_f32 v[72:73], v[14:15], v[14:15]
	v_mov_b32_e32 v79, v80
	v_pk_mul_f32 v[80:81], v[12:13], v[12:13]
	v_mul_f32_e32 v90, v55, v55
	v_pk_mov_b32 v[82:83], v[80:81], v[72:73] op_sel:[1,0]
	v_mov_b32_e32 v81, v73
	v_pk_add_f32 v[72:73], v[82:83], v[80:81]
	v_pk_mul_f32 v[80:81], v[22:23], v[22:23]
	v_pk_mul_f32 v[82:83], v[20:21], v[20:21]
	v_pk_add_f32 v[72:73], v[72:73], v[72:73] op_sel:[0,1] op_sel_hi:[1,0]
	v_pk_mov_b32 v[84:85], v[82:83], v[80:81] op_sel:[1,0]
	v_mov_b32_e32 v83, v81
	v_pk_add_f32 v[80:81], v[84:85], v[82:83]
	v_mul_f32_e32 v82, v56, v56
	v_mul_f32_e32 v83, v57, v57
	v_pk_add_f32 v[80:81], v[80:81], v[80:81] op_sel:[0,1] op_sel_hi:[1,0]
	v_mov_b32_e32 v73, v82
	v_mov_b32_e32 v81, v83
	v_pk_add_f32 v[72:73], v[72:73], v[80:81]
	v_mul_f32_e32 v80, v45, v45
	v_mul_f32_e32 v82, v47, v47
	v_mul_f32_e32 v84, v58, v58
	v_mul_f32_e32 v85, v59, v59
	v_pk_fma_f32 v[80:81], v[44:45], v[44:45], v[80:81] op_sel_hi:[1,1,0]
	v_pk_fma_f32 v[82:83], v[46:47], v[46:47], v[82:83] op_sel_hi:[1,1,0]
	v_mov_b32_e32 v81, v84
	v_mov_b32_e32 v83, v85
	v_pk_add_f32 v[80:81], v[80:81], v[82:83]
	v_pk_mul_f32 v[82:83], v[0:1], v[0:1]
	v_pk_add_f32 v[72:73], v[72:73], v[80:81]
	v_pk_mul_f32 v[80:81], v[2:3], v[2:3]
	s_nop 0
	v_pk_mov_b32 v[84:85], v[82:83], v[80:81] op_sel:[1,0]
	v_mov_b32_e32 v83, v81
	v_pk_add_f32 v[80:81], v[84:85], v[82:83]
	v_pk_mul_f32 v[82:83], v[10:11], v[10:11]
	v_pk_mul_f32 v[84:85], v[8:9], v[8:9]
	v_pk_add_f32 v[80:81], v[80:81], v[80:81] op_sel:[0,1] op_sel_hi:[1,0]
	v_pk_mov_b32 v[86:87], v[84:85], v[82:83] op_sel:[1,0]
	v_mov_b32_e32 v85, v83
	v_pk_add_f32 v[82:83], v[86:87], v[84:85]
	v_mul_f32_e32 v84, v60, v60
	v_mul_f32_e32 v85, v61, v61
	v_pk_add_f32 v[82:83], v[82:83], v[82:83] op_sel:[0,1] op_sel_hi:[1,0]
	v_mov_b32_e32 v81, v84
	v_mov_b32_e32 v83, v85
	v_pk_add_f32 v[80:81], v[80:81], v[82:83]
	v_mul_f32_e32 v82, v33, v33
	v_mul_f32_e32 v84, v35, v35
	v_mul_f32_e32 v86, v62, v62
	v_mul_f32_e32 v87, v63, v63
	v_pk_fma_f32 v[82:83], v[32:33], v[32:33], v[82:83] op_sel_hi:[1,1,0]
	v_pk_fma_f32 v[84:85], v[34:35], v[34:35], v[84:85] op_sel_hi:[1,1,0]
	v_mov_b32_e32 v83, v86
	v_mov_b32_e32 v85, v87
	v_pk_add_f32 v[82:83], v[82:83], v[84:85]
	v_pk_add_f32 v[84:85], v[74:75], v[74:75] op_sel:[0,1] op_sel_hi:[1,0]
	v_pk_add_f32 v[80:81], v[80:81], v[82:83]
	v_mov_b32_e32 v82, v72
	v_mov_b32_e32 v83, v80
	v_mov_b32_e32 v80, v73
	s_nop 1
	v_mov_b32_e32 v72, v208
	v_mov_b32_e32 v73, v209
	v_mov_b32_e32 v74, v210
	v_mov_b32_e32 v75, v211
	v_pk_add_f32 v[80:81], v[82:83], v[80:81]
	v_mov_b32_e32 v85, v88
	ds_bpermute_b32 v83, v104, v81
	ds_bpermute_b32 v82, v104, v80
	v_pk_add_f32 v[78:79], v[78:79], v[84:85]
	v_mul_f32_e32 v84, v41, v41
	v_mul_f32_e32 v86, v43, v43
	v_pk_fma_f32 v[84:85], v[40:41], v[40:41], v[84:85] op_sel_hi:[1,1,0]
	v_pk_fma_f32 v[86:87], v[42:43], v[42:43], v[86:87] op_sel_hi:[1,1,0]
	v_mov_b32_e32 v85, v89
	v_mov_b32_e32 v87, v90
	v_pk_add_f32 v[84:85], v[84:85], v[86:87]
	s_waitcnt lgkmcnt(0)
; __device__ __forceinline__ void ew_post(const bf16* Y, const float* xin, float* xout, const float* gpost, const float* gnext, bf16* H, int gw, int ngw, int lane) {
;     ...
;             for (int q = 0; q < EW_NR; ++q) r2[q] = rsqrtf(wave_sum(s2[q]) * (1.f / DM) + RMS_EPS);
	v_pk_add_f32 v[80:81], v[80:81], v[82:83]
	v_pk_add_f32 v[78:79], v[78:79], v[84:85]
	v_mov_b32_e32 v84, v76
	v_mov_b32_e32 v85, v78
	v_mov_b32_e32 v78, v77
	ds_bpermute_b32 v83, v105, v81
	ds_bpermute_b32 v82, v105, v80
	v_pk_add_f32 v[76:77], v[84:85], v[78:79]
	ds_bpermute_b32 v79, v104, v77
	ds_bpermute_b32 v78, v104, v76
	s_waitcnt lgkmcnt(2)
	v_pk_add_f32 v[80:81], v[80:81], v[82:83]
	ds_bpermute_b32 v83, v106, v81
	ds_bpermute_b32 v82, v106, v80
	s_waitcnt lgkmcnt(2)
	v_pk_add_f32 v[76:77], v[76:77], v[78:79]
	ds_bpermute_b32 v79, v105, v77
	ds_bpermute_b32 v78, v105, v76
	s_waitcnt lgkmcnt(2)
	v_pk_add_f32 v[80:81], v[80:81], v[82:83]
	ds_bpermute_b32 v83, v107, v81
	ds_bpermute_b32 v82, v107, v80
	s_waitcnt lgkmcnt(2)
	v_pk_add_f32 v[76:77], v[76:77], v[78:79]
	ds_bpermute_b32 v79, v106, v77
	ds_bpermute_b32 v78, v106, v76
	s_waitcnt lgkmcnt(2)
	v_pk_add_f32 v[80:81], v[80:81], v[82:83]
	ds_bpermute_b32 v83, v108, v81
	ds_bpermute_b32 v82, v108, v80
	s_waitcnt lgkmcnt(2)
	v_pk_add_f32 v[76:77], v[76:77], v[78:79]
	ds_bpermute_b32 v79, v107, v77
	ds_bpermute_b32 v78, v107, v76
	s_waitcnt lgkmcnt(2)
	v_pk_add_f32 v[80:81], v[80:81], v[82:83]
	ds_bpermute_b32 v83, v109, v81
	ds_bpermute_b32 v82, v109, v80
	s_waitcnt lgkmcnt(2)
	v_pk_add_f32 v[76:77], v[76:77], v[78:79]
	ds_bpermute_b32 v79, v108, v77
	ds_bpermute_b32 v78, v108, v76
	s_waitcnt lgkmcnt(2)
	v_pk_add_f32 v[80:81], v[80:81], v[82:83]
	v_mov_b64_e32 v[82:83], s[24:25]
	v_pk_fma_f32 v[80:81], v[80:81], s[44:45], v[82:83] op_sel_hi:[1,0,0]
	s_waitcnt lgkmcnt(0)
	v_pk_add_f32 v[76:77], v[76:77], v[78:79]
	v_mul_f32_e32 v84, 0x4b800000, v81
	v_cmp_gt_f32_e32 vcc, s3, v81
	ds_bpermute_b32 v79, v109, v77
	ds_bpermute_b32 v78, v109, v76
	v_cndmask_b32_e32 v81, v81, v84, vcc
	v_rsq_f32_e32 v81, v81
	v_mul_f32_e32 v84, 0x4b800000, v80
	v_cmp_gt_f32_e64 s[4:5], s3, v80
	s_waitcnt lgkmcnt(0)
; __device__ __forceinline__ unsigned pk2(float lo, float hi) { f32v2 v = {lo, hi}; bf16v2 r = __builtin_convertvector(v, bf16v2); return __builtin_bit_cast(unsigned, r); }
; __device__ __forceinline__ void ew_post(const bf16* Y, const float* xin, float* xout, const float* gpost, const float* gnext, bf16* H, int gw, int ngw, int lane) {
;     ...
;             for (int q = 0; q < EW_NR; ++q) r2[q] = rsqrtf(wave_sum(s2[q]) * (1.f / DM) + RMS_EPS);
; #pragma unroll
;             for (int j = 0; j < 4; ++j) { const f32x4 g = *((const f32x4*)gnext + lane + 64 * j);
; #pragma unroll
;                 for (int q = 0; q < EW_NR; ++q) { v2u w; w.x = pk2(xv[q][j].x * r2[q] * g.x, xv[q][j].y * r2[q] * g.y); w.y = pk2(xv[q][j].z * r2[q] * g.z, xv[q][j].w * r2[q] * g.w);
;                     *((v2u*)(H + (size_t)(m0 + q) * DM) + lane + 64 * j) = w; } }
	v_pk_add_f32 v[76:77], v[76:77], v[78:79]
	v_cndmask_b32_e64 v80, v80, v84, s[4:5]
	v_rsq_f32_e32 v84, v80
	v_mul_f32_e32 v80, 0x45800000, v81
	v_pk_fma_f32 v[76:77], v[76:77], s[44:45], v[82:83] op_sel_hi:[1,0,0]
	v_cndmask_b32_e32 v80, v81, v80, vcc
	v_mul_f32_e32 v78, 0x4b800000, v77
	v_cmp_gt_f32_e32 vcc, s3, v77
	v_cmp_gt_f32_e64 s[6:7], s3, v76
	v_mul_f32_e32 v81, 0x45800000, v84
	v_cndmask_b32_e32 v77, v77, v78, vcc
	v_rsq_f32_e32 v77, v77
	v_mul_f32_e32 v78, 0x4b800000, v76
	v_cndmask_b32_e64 v76, v76, v78, s[6:7]
	v_rsq_f32_e32 v79, v76
	v_mul_f32_e32 v78, 0x45800000, v77
	v_pk_mul_f32 v[0:1], v[0:1], v[80:81] op_sel_hi:[1,0]
	v_pk_mul_f32 v[2:3], v[2:3], v[80:81] op_sel_hi:[1,0]
	v_cndmask_b32_e64 v76, v84, v81, s[4:5]
	v_cndmask_b32_e32 v78, v77, v78, vcc
	v_pk_mul_f32 v[0:1], v[0:1], v[72:73]
	v_pk_mul_f32 v[2:3], v[2:3], v[74:75]
	v_add_co_u32_e32 v84, vcc, s22, v68
	v_mul_f32_e32 v77, 0x45800000, v79
	v_cvt_pk_bf16_f32 v0, v0, v1
	v_cvt_pk_bf16_f32 v1, v2, v3
	v_addc_co_u32_e32 v85, vcc, -1, v69, vcc
	global_store_dwordx2 v[84:85], v[0:1], off offset:-3584 sc0 sc1
	v_pk_mul_f32 v[0:1], v[12:13], v[76:77] op_sel_hi:[1,0]
	v_pk_mul_f32 v[2:3], v[14:15], v[76:77] op_sel_hi:[1,0]
	v_pk_mul_f32 v[0:1], v[0:1], v[72:73]
	v_pk_mul_f32 v[2:3], v[2:3], v[74:75]
	v_cvt_pk_bf16_f32 v0, v0, v1
	v_cvt_pk_bf16_f32 v1, v2, v3
	global_store_dwordx2 v[84:85], v[0:1], off offset:-1536 sc0 sc1
	v_pk_mul_f32 v[0:1], v[16:17], v[78:79] op_sel_hi:[1,0]
	v_pk_mul_f32 v[2:3], v[18:19], v[78:79] op_sel_hi:[1,0]
	v_pk_mul_f32 v[0:1], v[72:73], v[0:1]
	v_pk_mul_f32 v[2:3], v[74:75], v[2:3]
	v_add_co_u32_e32 v12, vcc, s23, v68
	v_cndmask_b32_e64 v82, v79, v77, s[6:7]
	v_cvt_pk_bf16_f32 v0, v0, v1
	v_cvt_pk_bf16_f32 v1, v2, v3
	v_addc_co_u32_e32 v13, vcc, -1, v69, vcc
	global_store_dwordx2 v[12:13], v[0:1], off offset:-3584 sc0 sc1
	v_pk_mul_f32 v[0:1], v[4:5], v[82:83] op_sel_hi:[1,0]
	v_pk_mul_f32 v[2:3], v[6:7], v[82:83] op_sel_hi:[1,0]
	v_pk_mul_f32 v[0:1], v[72:73], v[0:1]
	v_pk_mul_f32 v[2:3], v[74:75], v[2:3]
	v_cvt_pk_bf16_f32 v0, v0, v1
	v_cvt_pk_bf16_f32 v1, v2, v3
	global_store_dwordx2 v[12:13], v[0:1], off offset:-1536 sc0 sc1
	s_nop 1
	v_mov_b32_e32 v0, v212
	v_mov_b32_e32 v1, v213
	v_mov_b32_e32 v2, v214
	v_mov_b32_e32 v3, v215
	v_pk_mul_f32 v[4:5], v[8:9], v[80:81] op_sel_hi:[1,0]
	v_pk_mul_f32 v[6:7], v[10:11], v[80:81] op_sel_hi:[1,0]
	v_pk_mul_f32 v[8:9], v[56:57], v[76:77] op_sel_hi:[1,0]
	v_pk_mul_f32 v[10:11], v[58:59], v[76:77] op_sel_hi:[1,0]
	v_pk_mul_f32 v[14:15], v[52:53], v[78:79] op_sel_hi:[1,0]
	v_pk_mul_f32 v[16:17], v[54:55], v[78:79] op_sel_hi:[1,0]
	v_pk_mul_f32 v[18:19], v[48:49], v[82:83] op_sel_hi:[1,0]
	v_pk_mul_f32 v[4:5], v[4:5], v[0:1]
	v_pk_mul_f32 v[6:7], v[6:7], v[2:3]
	v_cvt_pk_bf16_f32 v4, v4, v5
	v_cvt_pk_bf16_f32 v5, v6, v7
	global_store_dwordx2 v[84:85], v[4:5], off offset:-3072 sc0 sc1
	v_pk_mul_f32 v[4:5], v[20:21], v[76:77] op_sel_hi:[1,0]
	v_pk_mul_f32 v[6:7], v[22:23], v[76:77] op_sel_hi:[1,0]
	v_pk_mul_f32 v[4:5], v[4:5], v[0:1]
	v_pk_mul_f32 v[6:7], v[6:7], v[2:3]
	v_cvt_pk_bf16_f32 v4, v4, v5
	v_cvt_pk_bf16_f32 v5, v6, v7
	global_store_dwordx2 v[84:85], v[4:5], off offset:-1024 sc0 sc1
	v_pk_mul_f32 v[4:5], v[24:25], v[78:79] op_sel_hi:[1,0]
	v_pk_mul_f32 v[6:7], v[26:27], v[78:79] op_sel_hi:[1,0]
	v_pk_mul_f32 v[4:5], v[4:5], v[0:1]
	v_pk_mul_f32 v[6:7], v[6:7], v[2:3]
	v_cvt_pk_bf16_f32 v4, v4, v5
	v_cvt_pk_bf16_f32 v5, v6, v7
	global_store_dwordx2 v[12:13], v[4:5], off offset:-3072 sc0 sc1
	v_pk_mul_f32 v[4:5], v[28:29], v[82:83] op_sel_hi:[1,0]
	v_pk_mul_f32 v[6:7], v[34:35], v[80:81] op_sel_hi:[1,0]
	v_pk_mul_f32 v[0:1], v[0:1], v[4:5]
	v_pk_mul_f32 v[4:5], v[30:31], v[82:83] op_sel_hi:[1,0]
	v_cvt_pk_bf16_f32 v0, v0, v1
	v_pk_mul_f32 v[2:3], v[2:3], v[4:5]
	v_pk_mul_f32 v[4:5], v[32:33], v[80:81] op_sel_hi:[1,0]
	v_cvt_pk_bf16_f32 v1, v2, v3
	global_store_dwordx2 v[12:13], v[0:1], off offset:-1024 sc0 sc1
	s_nop 1
	v_mov_b32_e32 v0, v216
	v_mov_b32_e32 v1, v217
	v_mov_b32_e32 v2, v218
	v_mov_b32_e32 v3, v219
	v_pk_mul_f32 v[20:21], v[50:51], v[82:83] op_sel_hi:[1,0]
	v_pk_mul_f32 v[4:5], v[4:5], v[0:1]
	v_pk_mul_f32 v[6:7], v[6:7], v[2:3]
	v_cvt_pk_bf16_f32 v4, v4, v5
	v_cvt_pk_bf16_f32 v5, v6, v7
	global_store_dwordx2 v[84:85], v[4:5], off offset:-2560 sc0 sc1
	v_pk_mul_f32 v[4:5], v[44:45], v[76:77] op_sel_hi:[1,0]
	v_pk_mul_f32 v[6:7], v[46:47], v[76:77] op_sel_hi:[1,0]
	v_pk_mul_f32 v[4:5], v[4:5], v[0:1]
	v_pk_mul_f32 v[6:7], v[6:7], v[2:3]
	v_cvt_pk_bf16_f32 v4, v4, v5
	v_cvt_pk_bf16_f32 v5, v6, v7
	global_store_dwordx2 v[84:85], v[4:5], off offset:-512 sc0 sc1
	v_pk_mul_f32 v[4:5], v[40:41], v[78:79] op_sel_hi:[1,0]
	v_pk_mul_f32 v[6:7], v[42:43], v[78:79] op_sel_hi:[1,0]
	v_pk_mul_f32 v[4:5], v[4:5], v[0:1]
	v_pk_mul_f32 v[6:7], v[6:7], v[2:3]
	v_cvt_pk_bf16_f32 v4, v4, v5
	v_cvt_pk_bf16_f32 v5, v6, v7
	global_store_dwordx2 v[12:13], v[4:5], off offset:-2560 sc0 sc1
	v_pk_mul_f32 v[4:5], v[36:37], v[82:83] op_sel_hi:[1,0]
	v_pk_mul_f32 v[6:7], v[62:63], v[80:81] op_sel_hi:[1,0]
	v_pk_mul_f32 v[0:1], v[4:5], v[0:1]
	v_pk_mul_f32 v[4:5], v[38:39], v[82:83] op_sel_hi:[1,0]
	v_cvt_pk_bf16_f32 v0, v0, v1
	v_pk_mul_f32 v[2:3], v[4:5], v[2:3]
	v_pk_mul_f32 v[4:5], v[60:61], v[80:81] op_sel_hi:[1,0]
	v_cvt_pk_bf16_f32 v1, v2, v3
	global_store_dwordx2 v[12:13], v[0:1], off offset:-512 sc0 sc1
	s_nop 1
	v_mov_b32_e32 v0, v220
	v_mov_b32_e32 v1, v221
	v_mov_b32_e32 v2, v222
	v_mov_b32_e32 v3, v223
	v_pk_mul_f32 v[4:5], v[4:5], v[0:1]
	v_pk_mul_f32 v[6:7], v[6:7], v[2:3]
	v_pk_mul_f32 v[8:9], v[8:9], v[0:1]
	v_pk_mul_f32 v[10:11], v[10:11], v[2:3]
	v_pk_mul_f32 v[14:15], v[14:15], v[0:1]
	v_pk_mul_f32 v[16:17], v[16:17], v[2:3]
	v_pk_mul_f32 v[0:1], v[18:19], v[0:1]
	v_pk_mul_f32 v[2:3], v[20:21], v[2:3]
	v_cvt_pk_bf16_f32 v4, v4, v5
	v_cvt_pk_bf16_f32 v5, v6, v7
	v_cvt_pk_bf16_f32 v6, v8, v9
	v_cvt_pk_bf16_f32 v7, v10, v11
	v_cvt_pk_bf16_f32 v8, v14, v15
	v_cvt_pk_bf16_f32 v9, v16, v17
	v_cvt_pk_bf16_f32 v0, v0, v1
	v_cvt_pk_bf16_f32 v1, v2, v3
	global_store_dwordx2 v[84:85], v[4:5], off offset:-2048 sc0 sc1
	global_store_dwordx2 v[12:13], v[6:7], off offset:-4096 sc0 sc1
	global_store_dwordx2 v[12:13], v[8:9], off offset:-2048 sc0 sc1
	global_store_dwordx2 v[12:13], v[0:1], off sc0 sc1
	s_branch .LBB0_190

; __device__ __forceinline__ unsigned pk2(float lo, float hi) { f32v2 v = {lo, hi}; bf16v2 r = __builtin_convertvector(v, bf16v2); return __builtin_bit_cast(unsigned, r); }
; __device__ __forceinline__ void ew_init(const float* x, const float* gain, bf16* H, int gw, int ngw, int lane) {
;     ...
;     for (int m = gw; m < NTOK; m += ngw) {
;         const f32x4* xr = (const f32x4*)(x + (size_t)m * DM) + lane; f32x4 v[4]; float s = 0.f;
; #pragma unroll
;         for (int j = 0; j < 4; ++j) { v[j] = __builtin_nontemporal_load(xr + 64 * j); s += (v[j].x * v[j].x + v[j].y * v[j].y) + (v[j].z * v[j].z + v[j].w * v[j].w); }
;         const float rstd = rsqrtf(wave_sum(s) * (1.f / DM) + RMS_EPS);
;         v2u* o = (v2u*)(H + (size_t)m * DM) + lane;
; #pragma unroll
;         for (int j = 0; j < 4; ++j) { v2u w; w.x = pk2(v[j].x * rstd * g[j].x, v[j].y * rstd * g[j].y); w.y = pk2(v[j].z * rstd * g[j].z, v[j].w * rstd * g[j].w); o[64 * j] = w; }
;     }
.Lewi4_loop:
	v_lshl_add_u64 v[108:109], v[18:19], 0, s[16:17]
	v_lshl_add_u64 v[110:111], v[108:109], 0, s[16:17]
	v_lshl_add_u64 v[112:113], v[110:111], 0, s[16:17]
	global_load_dwordx4 v[26:29], v[18:19], off offset:-3072 nt
	global_load_dwordx4 v[30:33], v[18:19], off offset:-2048 nt
	global_load_dwordx4 v[34:37], v[18:19], off offset:-1024 nt
	global_load_dwordx4 v[38:41], v[18:19], off nt
	global_load_dwordx4 v[60:63], v[108:109], off offset:-3072 nt
	global_load_dwordx4 v[64:67], v[108:109], off offset:-2048 nt
	global_load_dwordx4 v[68:71], v[108:109], off offset:-1024 nt
	global_load_dwordx4 v[72:75], v[108:109], off nt
	global_load_dwordx4 v[76:79], v[110:111], off offset:-3072 nt
	global_load_dwordx4 v[80:83], v[110:111], off offset:-2048 nt
	global_load_dwordx4 v[84:87], v[110:111], off offset:-1024 nt
	global_load_dwordx4 v[88:91], v[110:111], off nt
	global_load_dwordx4 v[92:95], v[112:113], off offset:-3072 nt
	global_load_dwordx4 v[96:99], v[112:113], off offset:-2048 nt
	global_load_dwordx4 v[100:103], v[112:113], off offset:-1024 nt
	global_load_dwordx4 v[104:107], v[112:113], off nt
	v_lshl_add_u64 v[114:115], v[16:17], 0, s[14:15]
	v_lshl_add_u64 v[116:117], v[114:115], 0, s[14:15]
	v_lshl_add_u64 v[118:119], v[116:117], 0, s[14:15]
	s_waitcnt vmcnt(12)
	v_pk_mul_f32 v[42:43], v[28:29], v[28:29]
	v_pk_mul_f32 v[44:45], v[26:27], v[26:27]
	v_pk_mul_f32 v[46:47], v[32:33], v[32:33]
	v_pk_mul_f32 v[48:49], v[30:31], v[30:31]
	v_pk_mov_b32 v[54:55], v[44:45], v[42:43] op_sel:[1,0]
	v_mov_b32_e32 v45, v43
	v_pk_mov_b32 v[42:43], v[48:49], v[46:47] op_sel:[1,0]
	v_mov_b32_e32 v49, v47
	v_mul_f32_e32 v53, v38, v38
	v_mul_f32_e32 v50, v35, v35
	v_mul_f32_e32 v52, v37, v37
	v_pk_add_f32 v[44:45], v[54:55], v[44:45]
	v_pk_add_f32 v[42:43], v[42:43], v[48:49]
	v_mul_f32_e32 v56, v39, v39
	v_mul_f32_e32 v57, v40, v40
	v_mul_f32_e32 v58, v41, v41
	v_pk_fma_f32 v[46:47], v[34:35], v[34:35], v[50:51] op_sel_hi:[1,1,0]
	v_pk_fma_f32 v[50:51], v[36:37], v[36:37], v[52:53] op_sel_hi:[1,1,0]
	v_pk_add_f32 v[44:45], v[44:45], v[44:45] op_sel:[0,1] op_sel_hi:[1,0]
	v_pk_add_f32 v[42:43], v[42:43], v[42:43] op_sel:[0,1] op_sel_hi:[1,0]
	v_mov_b32_e32 v47, v57
	v_mov_b32_e32 v51, v58
	v_mov_b32_e32 v45, v53
	v_mov_b32_e32 v43, v56
	v_pk_add_f32 v[46:47], v[46:47], v[50:51]
	v_pk_add_f32 v[42:43], v[44:45], v[42:43]
	s_nop 0
	v_pk_add_f32 v[42:43], v[42:43], v[46:47]
	s_nop 0
	v_add_f32_e32 v42, v42, v43
	ds_bpermute_b32 v43, v20, v42
	s_waitcnt lgkmcnt(0)
	v_add_f32_e32 v42, v42, v43
	ds_bpermute_b32 v43, v21, v42
	s_waitcnt lgkmcnt(0)
	v_add_f32_e32 v42, v42, v43
	ds_bpermute_b32 v43, v22, v42
	s_waitcnt lgkmcnt(0)
	v_add_f32_e32 v42, v42, v43
	ds_bpermute_b32 v43, v23, v42
	s_waitcnt lgkmcnt(0)
	v_add_f32_e32 v42, v42, v43
	ds_bpermute_b32 v43, v24, v42
	s_waitcnt lgkmcnt(0)
	v_add_f32_e32 v42, v42, v43
	ds_bpermute_b32 v43, v25, v42
	s_waitcnt lgkmcnt(0)
	v_add_f32_e32 v42, v42, v43
	v_fmamk_f32 v42, v42, 0x3a800000, v185
	v_mul_f32_e32 v43, 0x4b800000, v42
	v_cmp_gt_f32_e32 vcc, s3, v42
	s_nop 1
	v_cndmask_b32_e32 v42, v42, v43, vcc
	v_rsq_f32_e32 v42, v42
	s_nop 0
	v_mul_f32_e32 v43, 0x45800000, v42
	v_cndmask_b32_e32 v42, v42, v43, vcc
	v_pk_mul_f32 v[26:27], v[26:27], v[42:43] op_sel_hi:[1,0]
	v_pk_mul_f32 v[28:29], v[28:29], v[42:43] op_sel_hi:[1,0]
	v_pk_mul_f32 v[30:31], v[30:31], v[42:43] op_sel_hi:[1,0]
	v_pk_mul_f32 v[32:33], v[32:33], v[42:43] op_sel_hi:[1,0]
	v_pk_mul_f32 v[34:35], v[34:35], v[42:43] op_sel_hi:[1,0]
	v_pk_mul_f32 v[36:37], v[36:37], v[42:43] op_sel_hi:[1,0]
	v_pk_mul_f32 v[38:39], v[38:39], v[42:43] op_sel_hi:[1,0]
	v_pk_mul_f32 v[40:41], v[40:41], v[42:43] op_sel_hi:[1,0]
	v_pk_mul_f32 v[26:27], v[12:13], v[26:27]
	v_pk_mul_f32 v[28:29], v[14:15], v[28:29]
	v_pk_mul_f32 v[30:31], v[8:9], v[30:31]
	v_pk_mul_f32 v[32:33], v[10:11], v[32:33]
	v_pk_mul_f32 v[34:35], v[4:5], v[34:35]
	v_pk_mul_f32 v[36:37], v[6:7], v[36:37]
	v_pk_mul_f32 v[38:39], v[0:1], v[38:39]
	v_pk_mul_f32 v[40:41], v[2:3], v[40:41]
	v_cvt_pk_bf16_f32 v26, v26, v27
	v_cvt_pk_bf16_f32 v27, v28, v29
	v_cvt_pk_bf16_f32 v28, v30, v31
	v_cvt_pk_bf16_f32 v29, v32, v33
	v_cvt_pk_bf16_f32 v30, v34, v35
	v_cvt_pk_bf16_f32 v31, v36, v37
	v_cvt_pk_bf16_f32 v32, v38, v39
	v_cvt_pk_bf16_f32 v33, v40, v41
	global_store_dwordx2 v[16:17], v[26:27], off sc0 sc1
	global_store_dwordx2 v[16:17], v[28:29], off offset:512 sc0 sc1
	global_store_dwordx2 v[16:17], v[30:31], off offset:1024 sc0 sc1
	global_store_dwordx2 v[16:17], v[32:33], off offset:1536 sc0 sc1
	s_waitcnt vmcnt(12)
	v_pk_mul_f32 v[42:43], v[62:63], v[62:63]
	v_pk_mul_f32 v[44:45], v[60:61], v[60:61]
	v_pk_mul_f32 v[46:47], v[66:67], v[66:67]
	v_pk_mul_f32 v[48:49], v[64:65], v[64:65]
	v_pk_mov_b32 v[54:55], v[44:45], v[42:43] op_sel:[1,0]
	v_mov_b32_e32 v45, v43
	v_pk_mov_b32 v[42:43], v[48:49], v[46:47] op_sel:[1,0]
	v_mov_b32_e32 v49, v47
	v_mul_f32_e32 v53, v72, v72
	v_mul_f32_e32 v50, v69, v69
	v_mul_f32_e32 v52, v71, v71
	v_pk_add_f32 v[44:45], v[54:55], v[44:45]
	v_pk_add_f32 v[42:43], v[42:43], v[48:49]
	v_mul_f32_e32 v56, v73, v73
	v_mul_f32_e32 v57, v74, v74
	v_mul_f32_e32 v58, v75, v75
	v_pk_fma_f32 v[46:47], v[68:69], v[68:69], v[50:51] op_sel_hi:[1,1,0]
	v_pk_fma_f32 v[50:51], v[70:71], v[70:71], v[52:53] op_sel_hi:[1,1,0]
	v_pk_add_f32 v[44:45], v[44:45], v[44:45] op_sel:[0,1] op_sel_hi:[1,0]
	v_pk_add_f32 v[42:43], v[42:43], v[42:43] op_sel:[0,1] op_sel_hi:[1,0]
	v_mov_b32_e32 v47, v57
	v_mov_b32_e32 v51, v58
	v_mov_b32_e32 v45, v53
	v_mov_b32_e32 v43, v56
	v_pk_add_f32 v[46:47], v[46:47], v[50:51]
	v_pk_add_f32 v[42:43], v[44:45], v[42:43]
	s_nop 0
	v_pk_add_f32 v[42:43], v[42:43], v[46:47]
	s_nop 0
	v_add_f32_e32 v42, v42, v43
	ds_bpermute_b32 v43, v20, v42
	s_waitcnt lgkmcnt(0)
; __device__ __forceinline__ unsigned pk2(float lo, float hi) { f32v2 v = {lo, hi}; bf16v2 r = __builtin_convertvector(v, bf16v2); return __builtin_bit_cast(unsigned, r); }
; __device__ __forceinline__ void ew_init(const float* x, const float* gain, bf16* H, int gw, int ngw, int lane) {
;     ...
;     for (int m = gw; m < NTOK; m += ngw) {
;         const f32x4* xr = (const f32x4*)(x + (size_t)m * DM) + lane; f32x4 v[4]; float s = 0.f;
; #pragma unroll
;         for (int j = 0; j < 4; ++j) { v[j] = __builtin_nontemporal_load(xr + 64 * j); s += (v[j].x * v[j].x + v[j].y * v[j].y) + (v[j].z * v[j].z + v[j].w * v[j].w); }
;         const float rstd = rsqrtf(wave_sum(s) * (1.f / DM) + RMS_EPS);
;         v2u* o = (v2u*)(H + (size_t)m * DM) + lane;
; #pragma unroll
;         for (int j = 0; j < 4; ++j) { v2u w; w.x = pk2(v[j].x * rstd * g[j].x, v[j].y * rstd * g[j].y); w.y = pk2(v[j].z * rstd * g[j].z, v[j].w * rstd * g[j].w); o[64 * j] = w; }
;     }
	v_add_f32_e32 v42, v42, v43
	ds_bpermute_b32 v43, v21, v42
	s_waitcnt lgkmcnt(0)
	v_add_f32_e32 v42, v42, v43
	ds_bpermute_b32 v43, v22, v42
	s_waitcnt lgkmcnt(0)
	v_add_f32_e32 v42, v42, v43
	ds_bpermute_b32 v43, v23, v42
	s_waitcnt lgkmcnt(0)
	v_add_f32_e32 v42, v42, v43
	ds_bpermute_b32 v43, v24, v42
	s_waitcnt lgkmcnt(0)
	v_add_f32_e32 v42, v42, v43
	ds_bpermute_b32 v43, v25, v42
	s_waitcnt lgkmcnt(0)
	v_add_f32_e32 v42, v42, v43
	v_fmamk_f32 v42, v42, 0x3a800000, v185
	v_mul_f32_e32 v43, 0x4b800000, v42
	v_cmp_gt_f32_e32 vcc, s3, v42
	s_nop 1
	v_cndmask_b32_e32 v42, v42, v43, vcc
	v_rsq_f32_e32 v42, v42
	s_nop 0
	v_mul_f32_e32 v43, 0x45800000, v42
	v_cndmask_b32_e32 v42, v42, v43, vcc
	v_pk_mul_f32 v[60:61], v[60:61], v[42:43] op_sel_hi:[1,0]
	v_pk_mul_f32 v[62:63], v[62:63], v[42:43] op_sel_hi:[1,0]
	v_pk_mul_f32 v[64:65], v[64:65], v[42:43] op_sel_hi:[1,0]
	v_pk_mul_f32 v[66:67], v[66:67], v[42:43] op_sel_hi:[1,0]
	v_pk_mul_f32 v[68:69], v[68:69], v[42:43] op_sel_hi:[1,0]
	v_pk_mul_f32 v[70:71], v[70:71], v[42:43] op_sel_hi:[1,0]
	v_pk_mul_f32 v[72:73], v[72:73], v[42:43] op_sel_hi:[1,0]
	v_pk_mul_f32 v[74:75], v[74:75], v[42:43] op_sel_hi:[1,0]
	v_pk_mul_f32 v[60:61], v[12:13], v[60:61]
	v_pk_mul_f32 v[62:63], v[14:15], v[62:63]
	v_pk_mul_f32 v[64:65], v[8:9], v[64:65]
	v_pk_mul_f32 v[66:67], v[10:11], v[66:67]
	v_pk_mul_f32 v[68:69], v[4:5], v[68:69]
	v_pk_mul_f32 v[70:71], v[6:7], v[70:71]
	v_pk_mul_f32 v[72:73], v[0:1], v[72:73]
	v_pk_mul_f32 v[74:75], v[2:3], v[74:75]
	v_cvt_pk_bf16_f32 v60, v60, v61
	v_cvt_pk_bf16_f32 v61, v62, v63
	v_cvt_pk_bf16_f32 v62, v64, v65
	v_cvt_pk_bf16_f32 v63, v66, v67
	v_cvt_pk_bf16_f32 v64, v68, v69
	v_cvt_pk_bf16_f32 v65, v70, v71
	v_cvt_pk_bf16_f32 v66, v72, v73
	v_cvt_pk_bf16_f32 v67, v74, v75
	global_store_dwordx2 v[114:115], v[60:61], off sc0 sc1
	global_store_dwordx2 v[114:115], v[62:63], off offset:512 sc0 sc1
	global_store_dwordx2 v[114:115], v[64:65], off offset:1024 sc0 sc1
	global_store_dwordx2 v[114:115], v[66:67], off offset:1536 sc0 sc1
	s_waitcnt vmcnt(12)
	v_pk_mul_f32 v[42:43], v[78:79], v[78:79]
	v_pk_mul_f32 v[44:45], v[76:77], v[76:77]
	v_pk_mul_f32 v[46:47], v[82:83], v[82:83]
	v_pk_mul_f32 v[48:49], v[80:81], v[80:81]
	v_pk_mov_b32 v[54:55], v[44:45], v[42:43] op_sel:[1,0]
	v_mov_b32_e32 v45, v43
	v_pk_mov_b32 v[42:43], v[48:49], v[46:47] op_sel:[1,0]
	v_mov_b32_e32 v49, v47
	v_mul_f32_e32 v53, v88, v88
	v_mul_f32_e32 v50, v85, v85
	v_mul_f32_e32 v52, v87, v87
	v_pk_add_f32 v[44:45], v[54:55], v[44:45]
	v_pk_add_f32 v[42:43], v[42:43], v[48:49]
	v_mul_f32_e32 v56, v89, v89
	v_mul_f32_e32 v57, v90, v90
	v_mul_f32_e32 v58, v91, v91
	v_pk_fma_f32 v[46:47], v[84:85], v[84:85], v[50:51] op_sel_hi:[1,1,0]
	v_pk_fma_f32 v[50:51], v[86:87], v[86:87], v[52:53] op_sel_hi:[1,1,0]
	v_pk_add_f32 v[44:45], v[44:45], v[44:45] op_sel:[0,1] op_sel_hi:[1,0]
	v_pk_add_f32 v[42:43], v[42:43], v[42:43] op_sel:[0,1] op_sel_hi:[1,0]
	v_mov_b32_e32 v47, v57
	v_mov_b32_e32 v51, v58
	v_mov_b32_e32 v45, v53
	v_mov_b32_e32 v43, v56
	v_pk_add_f32 v[46:47], v[46:47], v[50:51]
	v_pk_add_f32 v[42:43], v[44:45], v[42:43]
	s_nop 0
	v_pk_add_f32 v[42:43], v[42:43], v[46:47]
	s_nop 0
	v_add_f32_e32 v42, v42, v43
	ds_bpermute_b32 v43, v20, v42
	s_waitcnt lgkmcnt(0)
	v_add_f32_e32 v42, v42, v43
	ds_bpermute_b32 v43, v21, v42
	s_waitcnt lgkmcnt(0)
	v_add_f32_e32 v42, v42, v43
	ds_bpermute_b32 v43, v22, v42
	s_waitcnt lgkmcnt(0)
	v_add_f32_e32 v42, v42, v43
	ds_bpermute_b32 v43, v23, v42
	s_waitcnt lgkmcnt(0)
	v_add_f32_e32 v42, v42, v43
	ds_bpermute_b32 v43, v24, v42
	s_waitcnt lgkmcnt(0)
	v_add_f32_e32 v42, v42, v43
	ds_bpermute_b32 v43, v25, v42
	s_waitcnt lgkmcnt(0)
	v_add_f32_e32 v42, v42, v43
	v_fmamk_f32 v42, v42, 0x3a800000, v185
	v_mul_f32_e32 v43, 0x4b800000, v42
	v_cmp_gt_f32_e32 vcc, s3, v42
	s_nop 1
	v_cndmask_b32_e32 v42, v42, v43, vcc
	v_rsq_f32_e32 v42, v42
	s_nop 0
	v_mul_f32_e32 v43, 0x45800000, v42
	v_cndmask_b32_e32 v42, v42, v43, vcc
	v_pk_mul_f32 v[76:77], v[76:77], v[42:43] op_sel_hi:[1,0]
	v_pk_mul_f32 v[78:79], v[78:79], v[42:43] op_sel_hi:[1,0]
	v_pk_mul_f32 v[80:81], v[80:81], v[42:43] op_sel_hi:[1,0]
	v_pk_mul_f32 v[82:83], v[82:83], v[42:43] op_sel_hi:[1,0]
	v_pk_mul_f32 v[84:85], v[84:85], v[42:43] op_sel_hi:[1,0]
	v_pk_mul_f32 v[86:87], v[86:87], v[42:43] op_sel_hi:[1,0]
	v_pk_mul_f32 v[88:89], v[88:89], v[42:43] op_sel_hi:[1,0]
	v_pk_mul_f32 v[90:91], v[90:91], v[42:43] op_sel_hi:[1,0]
	v_pk_mul_f32 v[76:77], v[12:13], v[76:77]
	v_pk_mul_f32 v[78:79], v[14:15], v[78:79]
	v_pk_mul_f32 v[80:81], v[8:9], v[80:81]
	v_pk_mul_f32 v[82:83], v[10:11], v[82:83]
	v_pk_mul_f32 v[84:85], v[4:5], v[84:85]
	v_pk_mul_f32 v[86:87], v[6:7], v[86:87]
	v_pk_mul_f32 v[88:89], v[0:1], v[88:89]
	v_pk_mul_f32 v[90:91], v[2:3], v[90:91]
	v_cvt_pk_bf16_f32 v76, v76, v77
	v_cvt_pk_bf16_f32 v77, v78, v79
	v_cvt_pk_bf16_f32 v78, v80, v81
	v_cvt_pk_bf16_f32 v79, v82, v83
	v_cvt_pk_bf16_f32 v80, v84, v85
	v_cvt_pk_bf16_f32 v81, v86, v87
	v_cvt_pk_bf16_f32 v82, v88, v89
	v_cvt_pk_bf16_f32 v83, v90, v91
	global_store_dwordx2 v[116:117], v[76:77], off sc0 sc1
	global_store_dwordx2 v[116:117], v[78:79], off offset:512 sc0 sc1
	global_store_dwordx2 v[116:117], v[80:81], off offset:1024 sc0 sc1
	global_store_dwordx2 v[116:117], v[82:83], off offset:1536 sc0 sc1
	s_waitcnt vmcnt(12)
; __device__ __forceinline__ unsigned pk2(float lo, float hi) { f32v2 v = {lo, hi}; bf16v2 r = __builtin_convertvector(v, bf16v2); return __builtin_bit_cast(unsigned, r); }
; __device__ __forceinline__ void ew_init(const float* x, const float* gain, bf16* H, int gw, int ngw, int lane) {
;     ...
;     for (int m = gw; m < NTOK; m += ngw) {
;         const f32x4* xr = (const f32x4*)(x + (size_t)m * DM) + lane; f32x4 v[4]; float s = 0.f;
; #pragma unroll
;         for (int j = 0; j < 4; ++j) { v[j] = __builtin_nontemporal_load(xr + 64 * j); s += (v[j].x * v[j].x + v[j].y * v[j].y) + (v[j].z * v[j].z + v[j].w * v[j].w); }
;         const float rstd = rsqrtf(wave_sum(s) * (1.f / DM) + RMS_EPS);
;         v2u* o = (v2u*)(H + (size_t)m * DM) + lane;
; #pragma unroll
;         for (int j = 0; j < 4; ++j) { v2u w; w.x = pk2(v[j].x * rstd * g[j].x, v[j].y * rstd * g[j].y); w.y = pk2(v[j].z * rstd * g[j].z, v[j].w * rstd * g[j].w); o[64 * j] = w; }
;     }
	v_pk_mul_f32 v[42:43], v[94:95], v[94:95]
	v_pk_mul_f32 v[44:45], v[92:93], v[92:93]
	v_pk_mul_f32 v[46:47], v[98:99], v[98:99]
	v_pk_mul_f32 v[48:49], v[96:97], v[96:97]
	v_pk_mov_b32 v[54:55], v[44:45], v[42:43] op_sel:[1,0]
	v_mov_b32_e32 v45, v43
	v_pk_mov_b32 v[42:43], v[48:49], v[46:47] op_sel:[1,0]
	v_mov_b32_e32 v49, v47
	v_mul_f32_e32 v53, v104, v104
	v_mul_f32_e32 v50, v101, v101
	v_mul_f32_e32 v52, v103, v103
	v_pk_add_f32 v[44:45], v[54:55], v[44:45]
	v_pk_add_f32 v[42:43], v[42:43], v[48:49]
	v_mul_f32_e32 v56, v105, v105
	v_mul_f32_e32 v57, v106, v106
	v_mul_f32_e32 v58, v107, v107
	v_pk_fma_f32 v[46:47], v[100:101], v[100:101], v[50:51] op_sel_hi:[1,1,0]
	v_pk_fma_f32 v[50:51], v[102:103], v[102:103], v[52:53] op_sel_hi:[1,1,0]
	v_pk_add_f32 v[44:45], v[44:45], v[44:45] op_sel:[0,1] op_sel_hi:[1,0]
	v_pk_add_f32 v[42:43], v[42:43], v[42:43] op_sel:[0,1] op_sel_hi:[1,0]
	v_mov_b32_e32 v47, v57
	v_mov_b32_e32 v51, v58
	v_mov_b32_e32 v45, v53
	v_mov_b32_e32 v43, v56
	v_pk_add_f32 v[46:47], v[46:47], v[50:51]
	v_pk_add_f32 v[42:43], v[44:45], v[42:43]
	s_nop 0
	v_pk_add_f32 v[42:43], v[42:43], v[46:47]
	s_nop 0
	v_add_f32_e32 v42, v42, v43
	ds_bpermute_b32 v43, v20, v42
	s_waitcnt lgkmcnt(0)
	v_add_f32_e32 v42, v42, v43
	ds_bpermute_b32 v43, v21, v42
	s_waitcnt lgkmcnt(0)
	v_add_f32_e32 v42, v42, v43
	ds_bpermute_b32 v43, v22, v42
	s_waitcnt lgkmcnt(0)
	v_add_f32_e32 v42, v42, v43
	ds_bpermute_b32 v43, v23, v42
	s_waitcnt lgkmcnt(0)
	v_add_f32_e32 v42, v42, v43
	ds_bpermute_b32 v43, v24, v42
	s_waitcnt lgkmcnt(0)
	v_add_f32_e32 v42, v42, v43
	ds_bpermute_b32 v43, v25, v42
	s_waitcnt lgkmcnt(0)
	v_add_f32_e32 v42, v42, v43
	v_fmamk_f32 v42, v42, 0x3a800000, v185
	v_mul_f32_e32 v43, 0x4b800000, v42
	v_cmp_gt_f32_e32 vcc, s3, v42
	s_nop 1
	v_cndmask_b32_e32 v42, v42, v43, vcc
	v_rsq_f32_e32 v42, v42
	s_nop 0
	v_mul_f32_e32 v43, 0x45800000, v42
	v_cndmask_b32_e32 v42, v42, v43, vcc
	v_pk_mul_f32 v[92:93], v[92:93], v[42:43] op_sel_hi:[1,0]
	v_pk_mul_f32 v[94:95], v[94:95], v[42:43] op_sel_hi:[1,0]
	v_pk_mul_f32 v[96:97], v[96:97], v[42:43] op_sel_hi:[1,0]
	v_pk_mul_f32 v[98:99], v[98:99], v[42:43] op_sel_hi:[1,0]
	v_pk_mul_f32 v[100:101], v[100:101], v[42:43] op_sel_hi:[1,0]
	v_pk_mul_f32 v[102:103], v[102:103], v[42:43] op_sel_hi:[1,0]
	v_pk_mul_f32 v[104:105], v[104:105], v[42:43] op_sel_hi:[1,0]
	v_pk_mul_f32 v[106:107], v[106:107], v[42:43] op_sel_hi:[1,0]
	v_pk_mul_f32 v[92:93], v[12:13], v[92:93]
	v_pk_mul_f32 v[94:95], v[14:15], v[94:95]
	v_pk_mul_f32 v[96:97], v[8:9], v[96:97]
	v_pk_mul_f32 v[98:99], v[10:11], v[98:99]
	v_pk_mul_f32 v[100:101], v[4:5], v[100:101]
	v_pk_mul_f32 v[102:103], v[6:7], v[102:103]
	v_pk_mul_f32 v[104:105], v[0:1], v[104:105]
	v_pk_mul_f32 v[106:107], v[2:3], v[106:107]
	v_cvt_pk_bf16_f32 v92, v92, v93
	v_cvt_pk_bf16_f32 v93, v94, v95
	v_cvt_pk_bf16_f32 v94, v96, v97
	v_cvt_pk_bf16_f32 v95, v98, v99
	v_cvt_pk_bf16_f32 v96, v100, v101
	v_cvt_pk_bf16_f32 v97, v102, v103
	v_cvt_pk_bf16_f32 v98, v104, v105
	v_cvt_pk_bf16_f32 v99, v106, v107
	global_store_dwordx2 v[118:119], v[92:93], off sc0 sc1
	global_store_dwordx2 v[118:119], v[94:95], off offset:512 sc0 sc1
	global_store_dwordx2 v[118:119], v[96:97], off offset:1024 sc0 sc1
	global_store_dwordx2 v[118:119], v[98:99], off offset:1536 sc0 sc1
	v_lshl_add_u64 v[18:19], v[112:113], 0, s[16:17]
	v_lshl_add_u64 v[16:17], v[118:119], 0, s[14:15]
	s_addk_i32 s4, 0x2000
	s_cmpk_gt_i32 s4, 0x7fff
	s_cbranch_scc0 .Lewi4_loop
	s_branch .Lewi4_done
; __device__ __forceinline__ unsigned pk2(float lo, float hi) { f32v2 v = {lo, hi}; bf16v2 r = __builtin_convertvector(v, bf16v2); return __builtin_bit_cast(unsigned, r); }
; __device__ __forceinline__ void ew_init(const float* x, const float* gain, bf16* H, int gw, int ngw, int lane) {
;     ...
;     for (int m = gw; m < NTOK; m += ngw) {
;         const f32x4* xr = (const f32x4*)(x + (size_t)m * DM) + lane; f32x4 v[4]; float s = 0.f;
; #pragma unroll
;         for (int j = 0; j < 4; ++j) { v[j] = __builtin_nontemporal_load(xr + 64 * j); s += (v[j].x * v[j].x + v[j].y * v[j].y) + (v[j].z * v[j].z + v[j].w * v[j].w); }
;         const float rstd = rsqrtf(wave_sum(s) * (1.f / DM) + RMS_EPS);
;         v2u* o = (v2u*)(H + (size_t)m * DM) + lane;
; #pragma unroll
;         for (int j = 0; j < 4; ++j) { v2u w; w.x = pk2(v[j].x * rstd * g[j].x, v[j].y * rstd * g[j].y); w.y = pk2(v[j].z * rstd * g[j].z, v[j].w * rstd * g[j].w); o[64 * j] = w; }
;     }
.LBB0_197:
	global_load_dwordx4 v[26:29], v[18:19], off offset:-3072 nt
	global_load_dwordx4 v[30:33], v[18:19], off offset:-2048 nt
	global_load_dwordx4 v[34:37], v[18:19], off offset:-1024 nt
	global_load_dwordx4 v[38:41], v[18:19], off nt
	s_add_i32 s4, s4, s66
	v_lshl_add_u64 v[18:19], v[18:19], 0, s[16:17]
	s_cmpk_gt_i32 s4, 0x7fff
	s_waitcnt vmcnt(0)
	v_pk_mul_f32 v[42:43], v[28:29], v[28:29]
	v_pk_mul_f32 v[44:45], v[26:27], v[26:27]
	s_waitcnt vmcnt(2)
	v_pk_mul_f32 v[46:47], v[32:33], v[32:33]
	v_pk_mul_f32 v[48:49], v[30:31], v[30:31]
	v_pk_mov_b32 v[54:55], v[44:45], v[42:43] op_sel:[1,0]
	v_mov_b32_e32 v45, v43
	v_pk_mov_b32 v[42:43], v[48:49], v[46:47] op_sel:[1,0]
	v_mov_b32_e32 v49, v47
	s_waitcnt vmcnt(0)
	v_mul_f32_e32 v53, v38, v38
	v_mul_f32_e32 v50, v35, v35
	v_mul_f32_e32 v52, v37, v37
	v_pk_add_f32 v[44:45], v[54:55], v[44:45]
	v_pk_add_f32 v[42:43], v[42:43], v[48:49]
	v_mul_f32_e32 v56, v39, v39
	v_mul_f32_e32 v57, v40, v40
	v_mul_f32_e32 v58, v41, v41
	v_pk_fma_f32 v[46:47], v[34:35], v[34:35], v[50:51] op_sel_hi:[1,1,0]
	v_pk_fma_f32 v[50:51], v[36:37], v[36:37], v[52:53] op_sel_hi:[1,1,0]
	v_pk_add_f32 v[44:45], v[44:45], v[44:45] op_sel:[0,1] op_sel_hi:[1,0]
	v_pk_add_f32 v[42:43], v[42:43], v[42:43] op_sel:[0,1] op_sel_hi:[1,0]
	v_mov_b32_e32 v47, v57
	v_mov_b32_e32 v51, v58
	v_mov_b32_e32 v45, v53
	v_mov_b32_e32 v43, v56
	v_pk_add_f32 v[46:47], v[46:47], v[50:51]
	v_pk_add_f32 v[42:43], v[44:45], v[42:43]
	s_nop 0
	v_pk_add_f32 v[42:43], v[42:43], v[46:47]
	s_nop 0
	v_add_f32_e32 v42, v42, v43
	ds_bpermute_b32 v43, v20, v42
	s_waitcnt lgkmcnt(0)
	v_add_f32_e32 v42, v42, v43
	ds_bpermute_b32 v43, v21, v42
	s_waitcnt lgkmcnt(0)
	v_add_f32_e32 v42, v42, v43
	ds_bpermute_b32 v43, v22, v42
	s_waitcnt lgkmcnt(0)
	v_add_f32_e32 v42, v42, v43
	ds_bpermute_b32 v43, v23, v42
	s_waitcnt lgkmcnt(0)
	v_add_f32_e32 v42, v42, v43
	ds_bpermute_b32 v43, v24, v42
	s_waitcnt lgkmcnt(0)
	v_add_f32_e32 v42, v42, v43
	ds_bpermute_b32 v43, v25, v42
	s_waitcnt lgkmcnt(0)
	v_add_f32_e32 v42, v42, v43
	v_fmamk_f32 v42, v42, 0x3a800000, v185
	v_mul_f32_e32 v43, 0x4b800000, v42
	v_cmp_gt_f32_e32 vcc, s3, v42
	s_nop 1
	v_cndmask_b32_e32 v42, v42, v43, vcc
	v_rsq_f32_e32 v42, v42
	s_nop 0
	v_mul_f32_e32 v43, 0x45800000, v42
	v_cndmask_b32_e32 v42, v42, v43, vcc
	v_pk_mul_f32 v[26:27], v[26:27], v[42:43] op_sel_hi:[1,0]
	v_pk_mul_f32 v[28:29], v[28:29], v[42:43] op_sel_hi:[1,0]
	v_pk_mul_f32 v[30:31], v[30:31], v[42:43] op_sel_hi:[1,0]
	v_pk_mul_f32 v[32:33], v[32:33], v[42:43] op_sel_hi:[1,0]
	v_pk_mul_f32 v[34:35], v[34:35], v[42:43] op_sel_hi:[1,0]
	v_pk_mul_f32 v[36:37], v[36:37], v[42:43] op_sel_hi:[1,0]
	v_pk_mul_f32 v[38:39], v[38:39], v[42:43] op_sel_hi:[1,0]
	v_pk_mul_f32 v[40:41], v[40:41], v[42:43] op_sel_hi:[1,0]
	v_pk_mul_f32 v[26:27], v[12:13], v[26:27]
	v_pk_mul_f32 v[28:29], v[14:15], v[28:29]
	v_pk_mul_f32 v[30:31], v[8:9], v[30:31]
	v_pk_mul_f32 v[32:33], v[10:11], v[32:33]
	v_pk_mul_f32 v[34:35], v[4:5], v[34:35]
	v_pk_mul_f32 v[36:37], v[6:7], v[36:37]
	v_pk_mul_f32 v[38:39], v[0:1], v[38:39]
	v_pk_mul_f32 v[40:41], v[2:3], v[40:41]
	v_cvt_pk_bf16_f32 v26, v26, v27
	v_cvt_pk_bf16_f32 v27, v28, v29
	v_cvt_pk_bf16_f32 v28, v30, v31
	v_cvt_pk_bf16_f32 v29, v32, v33
	v_cvt_pk_bf16_f32 v30, v34, v35
	v_cvt_pk_bf16_f32 v31, v36, v37
	v_cvt_pk_bf16_f32 v32, v38, v39
	v_cvt_pk_bf16_f32 v33, v40, v41
	global_store_dwordx2 v[16:17], v[26:27], off sc0 sc1
	global_store_dwordx2 v[16:17], v[28:29], off offset:512 sc0 sc1
	global_store_dwordx2 v[16:17], v[30:31], off offset:1024 sc0 sc1
	global_store_dwordx2 v[16:17], v[32:33], off offset:1536 sc0 sc1
	v_lshl_add_u64 v[16:17], v[16:17], 0, s[14:15]
	s_cbranch_scc0 .LBB0_197

; __device__ __forceinline__ void ew_post(const bf16* Y, const float* xin, float* xout, const float* gpost, const float* gnext, bf16* H, int gw, int ngw, int lane) {
;     ...
;         for (int q = 0; q < EW_NR; ++q) { const v2u* yr = (const v2u*)(Y + (size_t)(m0 + q) * DM) + lane; const f32x4* xr = (const f32x4*)(xin + (size_t)(m0 + q) * DM) + lane;
; #pragma unroll
;             for (int j = 0; j < 4; ++j) { const v2u w = __builtin_nontemporal_load(yr + 64 * j); y[q][j] = (f32x4){bf_lo(w.x), bf_hi(w.x), bf_lo(w.y), bf_hi(w.y)}; xv[q][j] = __builtin_nontemporal_load(xr + 64 * j); } }
; #pragma unroll
;         for (int q = 0; q < EW_NR; ++q) { s[q] = 0.f;
; #pragma unroll
;             for (int j = 0; j < 4; ++j) s[q] += (y[q][j].x * y[q][j].x + y[q][j].y * y[q][j].y) + (y[q][j].z * y[q][j].z + y[q][j].w * y[q][j].w); }
;         float rstd[EW_NR], s2[EW_NR];
; #pragma unroll
;         for (int q = 0; q < EW_NR; ++q) { rstd[q] = rsqrtf(wave_sum(s[q]) * (1.f / DM) + RMS_EPS); s2[q] = 0.f; }
.LBB0_209:
	v_add_co_u32_e32 v8, vcc, 0xfffff000, v72
	global_load_dwordx2 v[38:39], v[72:73], off offset:-4096 nt
	global_load_dwordx2 v[40:41], v[72:73], off offset:-2048 nt
	v_addc_co_u32_e32 v9, vcc, -1, v73, vcc
	global_load_dwordx2 v[42:43], v[72:73], off nt
	global_load_dwordx2 v[48:49], v[8:9], off offset:-2048 nt
	global_load_dwordx2 v[50:51], v[8:9], off offset:-3584 nt
	global_load_dwordx2 v[52:53], v[8:9], off offset:-3072 nt
	global_load_dwordx2 v[54:55], v[8:9], off offset:-2560 nt
	v_lshl_add_u64 v[10:11], s[12:13], 0, v[178:179]
	global_load_dwordx2 v[96:97], v[72:73], off offset:-3584 nt
	global_load_dwordx2 v[106:107], v[72:73], off offset:-3072 nt
	global_load_dwordx2 v[98:99], v[72:73], off offset:-2560 nt
	global_load_dwordx2 v[108:109], v[72:73], off offset:-1536 nt
	global_load_dwordx2 v[66:67], v[72:73], off offset:-1024 nt
	global_load_dwordx2 v[46:47], v[72:73], off offset:-512 nt
	global_load_dwordx2 v[90:91], v[8:9], off offset:-1536 nt
	global_load_dwordx4 v[20:23], v[10:11], off nt
	global_load_dwordx4 v[12:15], v[10:11], off offset:1024 nt
	global_load_dwordx4 v[4:7], v[10:11], off offset:2048 nt
	global_load_dwordx4 v[0:3], v[10:11], off offset:3072 nt
	global_load_dwordx2 v[92:93], v[8:9], off offset:-1024 nt
	global_load_dwordx2 v[104:105], v[8:9], off offset:-512 nt
	v_add_co_u32_e64 v36, s[4:5], s24, v10
	v_add_co_u32_e32 v44, vcc, s22, v10
	s_nop 0
	v_addc_co_u32_e64 v37, s[4:5], 0, v11, s[4:5]
	s_mov_b64 s[4:5], vcc
	v_add_co_u32_e32 v64, vcc, s23, v10
	v_addc_co_u32_e64 v45, s[4:5], 0, v11, s[4:5]
	global_load_dwordx4 v[28:31], v[36:37], off nt
	v_addc_co_u32_e32 v65, vcc, 0, v11, vcc
	global_load_dwordx4 v[16:19], v[44:45], off offset:1024 nt
	global_load_dwordx4 v[8:11], v[44:45], off offset:2048 nt
	global_load_dwordx4 v[24:27], v[64:65], off offset:-4096 nt
	global_load_dwordx4 v[32:35], v[64:65], off nt
	s_nop 1
	v_mov_b32_e32 v136, v156
	v_mov_b32_e32 v137, v157
	v_mov_b32_e32 v138, v158
	v_mov_b32_e32 v139, v159
	v_mov_b64_e32 v[148:149], s[26:27]
	global_load_dwordx4 v[192:195], v[44:45], off offset:3072 nt
	global_load_dwordx4 v[196:199], v[64:65], off offset:1024 nt
	global_load_dwordx4 v[200:203], v[64:65], off offset:2048 nt
	global_load_dwordx4 v[204:207], v[64:65], off offset:3072 nt
	global_load_dwordx4 v[208:211], v[36:37], off offset:1024 nt
	global_load_dwordx4 v[212:215], v[36:37], off offset:2048 nt
	global_load_dwordx4 v[216:219], v[36:37], off offset:3072 nt
	s_waitcnt vmcnt(0)
	v_and_b32_e32 v121, 0xffff0000, v97
	v_and_b32_e32 v119, 0xffff0000, v96
	v_lshlrev_b32_e32 v120, 16, v97
	v_lshlrev_b32_e32 v118, 16, v96
	v_lshlrev_b32_e32 v59, 16, v38
	v_lshlrev_b32_e32 v77, 16, v40
	v_lshlrev_b32_e32 v87, 16, v48
	v_and_b32_e32 v101, 0xffff0000, v50
	v_and_b32_e32 v103, 0xffff0000, v51
	v_and_b32_e32 v75, 0xffff0000, v40
	v_lshlrev_b32_e32 v78, 16, v41
	v_and_b32_e32 v79, 0xffff0000, v41
	v_lshlrev_b32_e32 v83, 16, v42
	v_and_b32_e32 v81, 0xffff0000, v42
	v_lshlrev_b32_e32 v84, 16, v43
	v_and_b32_e32 v85, 0xffff0000, v43
	v_and_b32_e32 v63, 0xffff0000, v48
	v_lshlrev_b32_e32 v88, 16, v49
	v_and_b32_e32 v89, 0xffff0000, v49
	v_lshlrev_b32_e32 v100, 16, v50
	v_lshlrev_b32_e32 v102, 16, v51
	v_and_b32_e32 v41, 0xffff0000, v53
	v_and_b32_e32 v40, 0xffff0000, v52
	v_lshlrev_b32_e32 v48, 16, v54
	v_and_b32_e32 v49, 0xffff0000, v54
	v_mul_f32_e32 v42, v103, v103
	v_mul_f32_e32 v54, v101, v101
	v_mov_b32_e32 v43, v87
	v_and_b32_e32 v57, 0xffff0000, v38
	v_lshlrev_b32_e32 v60, 16, v39
	v_and_b32_e32 v61, 0xffff0000, v39
	v_lshlrev_b32_e32 v39, 16, v53
	v_lshlrev_b32_e32 v38, 16, v52
	v_lshlrev_b32_e32 v50, 16, v55
	v_and_b32_e32 v51, 0xffff0000, v55
	v_pk_mul_f32 v[52:53], v[40:41], v[40:41]
	v_pk_fma_f32 v[94:95], v[102:103], v[102:103], v[42:43] op_sel_hi:[1,1,0]
	v_pk_fma_f32 v[54:55], v[100:101], v[100:101], v[54:55] op_sel_hi:[1,1,0]
	v_pk_fma_f32 v[52:53], v[38:39], v[38:39], v[52:53]
	v_mov_b32_e32 v86, v54
	v_mov_b32_e32 v42, v94
	v_mul_f32_e32 v56, v63, v63
	v_pk_add_f32 v[54:55], v[54:55], v[94:95]
	v_pk_add_f32 v[52:53], v[52:53], v[52:53] op_sel:[0,1] op_sel_hi:[1,0]
	v_pk_mul_f32 v[42:43], v[86:87], v[42:43]
	v_mov_b32_e32 v53, v56
	v_mov_b32_e32 v55, v43
	v_pk_add_f32 v[42:43], v[54:55], v[52:53]
	v_mul_f32_e32 v52, v49, v49
	v_mul_f32_e32 v54, v51, v51
	v_mul_f32_e32 v58, v88, v88
	v_mul_f32_e32 v62, v89, v89
	v_pk_fma_f32 v[52:53], v[48:49], v[48:49], v[52:53] op_sel_hi:[1,1,0]
	v_pk_fma_f32 v[54:55], v[50:51], v[50:51], v[54:55] op_sel_hi:[1,1,0]
	v_mov_b32_e32 v53, v58
	v_mov_b32_e32 v55, v62
	v_pk_add_f32 v[52:53], v[52:53], v[54:55]
	v_and_b32_e32 v113, 0xffff0000, v91
	v_pk_add_f32 v[52:53], v[42:43], v[52:53]
	v_and_b32_e32 v111, 0xffff0000, v90
	v_lshlrev_b32_e32 v112, 16, v91
	v_mul_f32_e32 v42, v113, v113
	v_and_b32_e32 v95, 0xffff0000, v93
	v_and_b32_e32 v94, 0xffff0000, v92
	v_lshlrev_b32_e32 v110, 16, v90
	v_pk_fma_f32 v[54:55], v[112:113], v[112:113], v[42:43] op_sel_hi:[1,1,0]
	v_lshlrev_b32_e32 v43, 16, v93
	v_lshlrev_b32_e32 v42, 16, v92
	v_pk_mul_f32 v[90:91], v[94:95], v[94:95]
	v_mul_f32_e32 v56, v111, v111
	v_pk_fma_f32 v[114:115], v[42:43], v[42:43], v[90:91]
	v_lshlrev_b32_e32 v90, 16, v104
	v_and_b32_e32 v91, 0xffff0000, v104
	v_lshlrev_b32_e32 v92, 16, v105
	v_and_b32_e32 v93, 0xffff0000, v105
	v_pk_fma_f32 v[104:105], v[110:111], v[110:111], v[56:57] op_sel_hi:[1,1,0]
	v_mov_b32_e32 v116, v54
	v_mov_b32_e32 v58, v104
	v_mov_b32_e32 v117, v59
	v_pk_add_f32 v[54:55], v[104:105], v[54:55]
	v_pk_mul_f32 v[104:105], v[58:59], v[116:117]
	v_mul_f32_e32 v62, v57, v57
	v_mov_b32_e32 v55, v105
	v_pk_add_f32 v[104:105], v[114:115], v[114:115] op_sel:[0,1] op_sel_hi:[1,0]
	v_mul_f32_e32 v56, v91, v91
	v_mov_b32_e32 v105, v62
	v_pk_add_f32 v[54:55], v[54:55], v[104:105]
	v_pk_fma_f32 v[104:105], v[90:91], v[90:91], v[56:57] op_sel_hi:[1,1,0]
	v_mul_f32_e32 v56, v93, v93
	v_mul_f32_e32 v74, v60, v60
	v_mul_f32_e32 v76, v61, v61
	v_pk_fma_f32 v[114:115], v[92:93], v[92:93], v[56:57] op_sel_hi:[1,1,0]
	v_mov_b32_e32 v105, v74
	v_mov_b32_e32 v115, v76
	v_pk_add_f32 v[104:105], v[104:105], v[114:115]
	v_mov_b32_e32 v143, v52
	v_pk_add_f32 v[54:55], v[54:55], v[104:105]
	v_mul_f32_e32 v56, v121, v121
	v_mov_b32_e32 v142, v54
	v_mov_b32_e32 v52, v55
	v_pk_add_f32 v[52:53], v[142:143], v[52:53]
	ds_bpermute_b32 v55, v130, v53
	ds_bpermute_b32 v54, v130, v52
	v_pk_fma_f32 v[114:115], v[120:121], v[120:121], v[56:57] op_sel_hi:[1,1,0]
	v_lshlrev_b32_e32 v105, 16, v107
	v_lshlrev_b32_e32 v104, 16, v106
	v_and_b32_e32 v107, 0xffff0000, v107
	v_and_b32_e32 v106, 0xffff0000, v106
	v_mul_f32_e32 v56, v119, v119
	v_pk_mul_f32 v[96:97], v[106:107], v[106:107]
	v_pk_fma_f32 v[122:123], v[118:119], v[118:119], v[56:57] op_sel_hi:[1,1,0]
	s_waitcnt lgkmcnt(0)
; __device__ __forceinline__ void ew_post(const bf16* Y, const float* xin, float* xout, const float* gpost, const float* gnext, bf16* H, int gw, int ngw, int lane) {
;     ...
;             for (int j = 0; j < 4; ++j) s[q] += (y[q][j].x * y[q][j].x + y[q][j].y * y[q][j].y) + (y[q][j].z * y[q][j].z + y[q][j].w * y[q][j].w); }
;         float rstd[EW_NR], s2[EW_NR];
; #pragma unroll
;         for (int q = 0; q < EW_NR; ++q) { rstd[q] = rsqrtf(wave_sum(s[q]) * (1.f / DM) + RMS_EPS); s2[q] = 0.f; }
; #pragma unroll
;         for (int j = 0; j < 4; ++j) { const f32x4 g = *((const f32x4*)gpost + lane + 64 * j);
; #pragma unroll
;             for (int q = 0; q < EW_NR; ++q) { xv[q][j] = xv[q][j] + y[q][j] * rstd[q] * g; __builtin_nontemporal_store(xv[q][j], (f32x4*)(xout + (size_t)(m0 + q) * DM) + lane + 64 * j);
	v_pk_add_f32 v[52:53], v[52:53], v[54:55]
	v_pk_fma_f32 v[116:117], v[104:105], v[104:105], v[96:97]
	v_mov_b32_e32 v76, v122
	v_mov_b32_e32 v124, v114
	v_mov_b32_e32 v125, v77
	ds_bpermute_b32 v55, v131, v53
	ds_bpermute_b32 v54, v131, v52
	v_and_b32_e32 v97, 0xffff0000, v98
	v_mul_f32_e32 v58, v75, v75
	v_pk_add_f32 v[114:115], v[122:123], v[114:115]
	v_pk_mul_f32 v[122:123], v[76:77], v[124:125]
	v_pk_add_f32 v[116:117], v[116:117], v[116:117] op_sel:[0,1] op_sel_hi:[1,0]
	v_lshlrev_b32_e32 v96, 16, v98
	v_lshlrev_b32_e32 v98, 16, v99
	v_and_b32_e32 v99, 0xffff0000, v99
	v_mov_b32_e32 v115, v123
	v_mov_b32_e32 v117, v58
	v_mul_f32_e32 v56, v97, v97
	v_pk_add_f32 v[114:115], v[114:115], v[116:117]
	v_pk_fma_f32 v[116:117], v[96:97], v[96:97], v[56:57] op_sel_hi:[1,1,0]
	v_mul_f32_e32 v56, v99, v99
	v_mul_f32_e32 v62, v78, v78
	v_mul_f32_e32 v74, v79, v79
	v_pk_fma_f32 v[122:123], v[98:99], v[98:99], v[56:57] op_sel_hi:[1,1,0]
	v_mov_b32_e32 v117, v62
	v_mov_b32_e32 v123, v74
	s_waitcnt lgkmcnt(0)
	v_pk_add_f32 v[52:53], v[52:53], v[54:55]
	v_pk_add_f32 v[116:117], v[116:117], v[122:123]
	v_and_b32_e32 v123, 0xffff0000, v108
	v_and_b32_e32 v125, 0xffff0000, v109
	ds_bpermute_b32 v55, v132, v53
	ds_bpermute_b32 v54, v132, v52
	v_pk_add_f32 v[128:129], v[114:115], v[116:117]
	v_lshlrev_b32_e32 v122, 16, v108
	v_lshlrev_b32_e32 v124, 16, v109
	v_mul_f32_e32 v56, v125, v125
	v_and_b32_e32 v117, 0xffff0000, v67
	v_and_b32_e32 v116, 0xffff0000, v66
	v_lshlrev_b32_e32 v108, 16, v46
	v_and_b32_e32 v109, 0xffff0000, v46
	v_mul_f32_e32 v46, v123, v123
	v_pk_fma_f32 v[140:141], v[124:125], v[124:125], v[56:57] op_sel_hi:[1,1,0]
	v_lshlrev_b32_e32 v115, 16, v67
	v_lshlrev_b32_e32 v114, 16, v66
	v_pk_mul_f32 v[66:67], v[116:117], v[116:117]
	v_lshlrev_b32_e32 v126, 16, v47
	v_and_b32_e32 v127, 0xffff0000, v47
	v_pk_fma_f32 v[46:47], v[122:123], v[122:123], v[46:47] op_sel_hi:[1,1,0]
	v_pk_fma_f32 v[66:67], v[114:115], v[114:115], v[66:67]
	v_mov_b32_e32 v82, v46
	v_mov_b32_e32 v142, v140
	v_mov_b32_e32 v143, v83
	v_mul_f32_e32 v56, v81, v81
	v_pk_add_f32 v[46:47], v[46:47], v[140:141]
	v_pk_mul_f32 v[140:141], v[82:83], v[142:143]
	v_pk_add_f32 v[66:67], v[66:67], v[66:67] op_sel:[0,1] op_sel_hi:[1,0]
	v_mov_b32_e32 v47, v141
	v_mov_b32_e32 v67, v56
	v_mul_f32_e32 v56, v109, v109
	s_waitcnt lgkmcnt(0)
	v_pk_add_f32 v[52:53], v[52:53], v[54:55]
	v_pk_add_f32 v[46:47], v[46:47], v[66:67]
	v_pk_fma_f32 v[66:67], v[108:109], v[108:109], v[56:57] op_sel_hi:[1,1,0]
	v_mul_f32_e32 v56, v127, v127
	ds_bpermute_b32 v55, v133, v53
	ds_bpermute_b32 v54, v133, v52
	v_mul_f32_e32 v58, v84, v84
	v_mul_f32_e32 v62, v85, v85
	v_pk_fma_f32 v[140:141], v[126:127], v[126:127], v[56:57] op_sel_hi:[1,1,0]
	v_mov_b32_e32 v67, v58
	v_mov_b32_e32 v141, v62
	v_pk_add_f32 v[66:67], v[66:67], v[140:141]
	v_mov_b32_e32 v74, v77
	v_pk_add_f32 v[46:47], v[46:47], v[66:67]
	s_waitcnt lgkmcnt(0)
	v_pk_add_f32 v[66:67], v[52:53], v[54:55]
	v_mov_b32_e32 v52, v46
	v_mov_b32_e32 v53, v128
	v_mov_b32_e32 v128, v47
	ds_bpermute_b32 v141, v134, v67
	ds_bpermute_b32 v140, v134, v66
	v_pk_add_f32 v[46:47], v[52:53], v[128:129]
	ds_bpermute_b32 v129, v130, v47
	ds_bpermute_b32 v128, v130, v46
	s_nop 1
	v_mov_b32_e32 v52, v192
	v_mov_b32_e32 v53, v193
	v_mov_b32_e32 v54, v194
	v_mov_b32_e32 v55, v195
	s_waitcnt lgkmcnt(2)
	v_pk_add_f32 v[44:45], v[66:67], v[140:141]
	ds_bpermute_b32 v67, v135, v45
	ds_bpermute_b32 v66, v135, v44
	s_waitcnt lgkmcnt(2)
	v_pk_add_f32 v[46:47], v[46:47], v[128:129]
	ds_bpermute_b32 v129, v131, v47
	ds_bpermute_b32 v128, v131, v46
	s_nop 1
	v_mov_b32_e32 v140, v196
	v_mov_b32_e32 v141, v197
	v_mov_b32_e32 v142, v198
	v_mov_b32_e32 v143, v199
	s_waitcnt lgkmcnt(2)
	v_pk_add_f32 v[44:45], v[44:45], v[66:67]
	v_mov_b32_e32 v80, v83
	v_pk_fma_f32 v[150:151], v[44:45], s[44:45], v[148:149] op_sel_hi:[1,0,0]
	s_waitcnt lgkmcnt(0)
	v_pk_add_f32 v[44:45], v[46:47], v[128:129]
	ds_bpermute_b32 v47, v132, v45
	ds_bpermute_b32 v46, v132, v44
	v_mul_f32_e32 v56, 0x4b800000, v151
	v_cmp_gt_f32_e32 vcc, s3, v151
	s_waitcnt lgkmcnt(0)
	v_pk_add_f32 v[128:129], v[44:45], v[46:47]
	ds_bpermute_b32 v145, v133, v129
	ds_bpermute_b32 v144, v133, v128
	v_cndmask_b32_e32 v56, v151, v56, vcc
	v_rsq_f32_e32 v56, v56
	s_nop 1
	v_mov_b32_e32 v44, v200
	v_mov_b32_e32 v45, v201
	v_mov_b32_e32 v46, v202
	v_mov_b32_e32 v47, v203
	s_nop 0
	s_nop 1
	v_mov_b32_e32 v64, v204
	v_mov_b32_e32 v65, v205
	v_mov_b32_e32 v66, v206
	v_mov_b32_e32 v67, v207
	s_waitcnt lgkmcnt(0)
	v_pk_add_f32 v[128:129], v[128:129], v[144:145]
	ds_bpermute_b32 v153, v134, v129
	ds_bpermute_b32 v152, v134, v128
	v_mul_f32_e32 v58, 0x45800000, v56
	v_cndmask_b32_e32 v56, v56, v58, vcc
	v_mul_f32_e32 v58, 0x4b800000, v150
	v_cmp_gt_f32_e32 vcc, s3, v150
	s_waitcnt lgkmcnt(0)
	v_pk_add_f32 v[128:129], v[128:129], v[152:153]
	ds_bpermute_b32 v153, v135, v129
	ds_bpermute_b32 v152, v135, v128
	v_cndmask_b32_e32 v58, v150, v58, vcc
	v_rsq_f32_e32 v58, v58
	v_pk_mul_f32 v[100:101], v[56:57], v[100:101] op_sel_hi:[0,1]
	v_pk_mul_f32 v[102:103], v[56:57], v[102:103] op_sel_hi:[0,1]
	s_waitcnt lgkmcnt(0)
; __device__ __forceinline__ void ew_post(const bf16* Y, const float* xin, float* xout, const float* gpost, const float* gnext, bf16* H, int gw, int ngw, int lane) {
;     ...
;         for (int j = 0; j < 4; ++j) { const f32x4 g = *((const f32x4*)gpost + lane + 64 * j);
; #pragma unroll
;             for (int q = 0; q < EW_NR; ++q) { xv[q][j] = xv[q][j] + y[q][j] * rstd[q] * g; __builtin_nontemporal_store(xv[q][j], (f32x4*)(xout + (size_t)(m0 + q) * DM) + lane + 64 * j);
;                 s2[q] += (xv[q][j].x * xv[q][j].x + xv[q][j].y * xv[q][j].y) + (xv[q][j].z * xv[q][j].z + xv[q][j].w * xv[q][j].w); } }
	v_pk_add_f32 v[128:129], v[128:129], v[152:153]
	v_pk_fma_f32 v[22:23], v[102:103], v[138:139], v[22:23]
	v_pk_fma_f32 v[128:129], v[128:129], s[44:45], v[148:149] op_sel_hi:[1,0,0]
	v_pk_fma_f32 v[20:21], v[100:101], v[136:137], v[20:21]
	v_mul_f32_e32 v62, 0x4b800000, v129
	v_cmp_gt_f32_e64 s[4:5], s3, v129
	s_nop 1
	v_mov_b32_e32 v100, v208
	v_mov_b32_e32 v101, v209
	v_mov_b32_e32 v102, v210
	v_mov_b32_e32 v103, v211
	s_nop 1
	v_mov_b32_e32 v144, v212
	v_mov_b32_e32 v145, v213
	v_mov_b32_e32 v146, v214
	v_mov_b32_e32 v147, v215
	v_cndmask_b32_e64 v62, v129, v62, s[4:5]
	v_rsq_f32_e32 v62, v62
	s_nop 1
	v_mov_b32_e32 v148, v216
	v_mov_b32_e32 v149, v217
	v_mov_b32_e32 v150, v218
	v_mov_b32_e32 v151, v219
	v_mul_f32_e32 v36, 0x45800000, v58
	v_cndmask_b32_e32 v58, v58, v36, vcc
	v_mul_f32_e32 v36, 0x45800000, v62
	v_cndmask_b32_e64 v76, v62, v36, s[4:5]
	v_mul_f32_e32 v36, 0x4b800000, v128
	v_cmp_gt_f32_e32 vcc, s3, v128
	v_pk_mul_f32 v[50:51], v[56:57], v[50:51] op_sel_hi:[0,1]
	v_pk_mul_f32 v[48:49], v[56:57], v[48:49] op_sel_hi:[0,1]
	v_cndmask_b32_e32 v36, v128, v36, vcc
	v_rsq_f32_e32 v62, v36
	v_pk_mul_f32 v[36:37], v[58:59], v[110:111] op_sel_hi:[0,1]
	v_pk_fma_f32 v[24:25], v[36:37], v[136:137], v[24:25]
	v_lshl_add_u64 v[128:129], s[10:11], 0, v[178:179]
	v_mul_f32_e32 v36, 0x45800000, v62
	v_pk_mul_f32 v[110:111], v[58:59], v[112:113] op_sel_hi:[0,1]
	v_cndmask_b32_e32 v82, v62, v36, vcc
	v_pk_mul_f32 v[36:37], v[76:77], v[118:119] op_sel_hi:[0,1]
	v_add_co_u32_e32 v118, vcc, s23, v128
	v_pk_fma_f32 v[26:27], v[110:111], v[138:139], v[26:27]
	v_pk_mul_f32 v[110:111], v[76:77], v[120:121] op_sel_hi:[0,1]
	v_addc_co_u32_e32 v119, vcc, 0, v129, vcc
	v_pk_fma_f32 v[34:35], v[138:139], v[110:111], v[34:35]
	v_pk_fma_f32 v[32:33], v[136:137], v[36:37], v[32:33]
	v_pk_mul_f32 v[36:37], v[82:83], v[122:123] op_sel_hi:[0,1]
	v_pk_mul_f32 v[110:111], v[82:83], v[124:125] op_sel_hi:[0,1]
	v_add_co_u32_e32 v120, vcc, s24, v128
	v_pk_fma_f32 v[30:31], v[138:139], v[110:111], v[30:31]
	v_pk_fma_f32 v[28:29], v[136:137], v[36:37], v[28:29]
	v_addc_co_u32_e32 v121, vcc, 0, v129, vcc
	global_store_dwordx4 v[128:129], v[20:23], off sc0 sc1 nt
	global_store_dwordx4 v[118:119], v[24:27], off offset:-4096 sc0 sc1 nt
	global_store_dwordx4 v[118:119], v[32:35], off sc0 sc1 nt
	global_store_dwordx4 v[120:121], v[28:31], off sc0 sc1 nt
	s_nop 1
	v_mov_b32_e32 v110, v160
	v_mov_b32_e32 v111, v161
	v_mov_b32_e32 v112, v162
	v_mov_b32_e32 v113, v163
	v_mov_b32_e32 v36, v39
	v_mov_b32_e32 v37, v41
	v_pk_mul_f32 v[36:37], v[56:57], v[36:37] op_sel_hi:[0,1]
	v_mov_b32_e32 v39, v40
	v_pk_mul_f32 v[38:39], v[56:57], v[38:39] op_sel_hi:[0,1]
	v_mov_b32_e32 v40, v115
	v_mov_b32_e32 v41, v117
	v_mov_b32_e32 v115, v116
	v_add_co_u32_e32 v122, vcc, s22, v128
	v_mov_b32_e32 v62, v87
	s_nop 0
	v_addc_co_u32_e32 v123, vcc, 0, v129, vcc
	v_pk_mul_f32 v[86:87], v[56:57], v[88:89] op_sel_hi:[0,1]
	v_pk_mul_f32 v[62:63], v[56:57], v[62:63] op_sel_hi:[0,1]
	v_mov_b32_e32 v56, v59
	v_pk_mul_f32 v[88:89], v[58:59], v[60:61] op_sel_hi:[0,1]
	s_andn2_b64 vcc, exec, s[30:31]
	v_pk_fma_f32 v[14:15], v[36:37], v[112:113], v[14:15]
	v_mov_b32_e32 v36, v43
	v_mov_b32_e32 v37, v95
	v_pk_mul_f32 v[36:37], v[58:59], v[36:37] op_sel_hi:[0,1]
	v_mov_b32_e32 v43, v94
	v_pk_fma_f32 v[12:13], v[38:39], v[110:111], v[12:13]
	v_pk_mul_f32 v[38:39], v[58:59], v[42:43] op_sel_hi:[0,1]
	v_pk_fma_f32 v[18:19], v[36:37], v[112:113], v[18:19]
	v_mov_b32_e32 v36, v105
	v_mov_b32_e32 v37, v107
	v_mov_b32_e32 v105, v106
	v_pk_fma_f32 v[16:17], v[38:39], v[110:111], v[16:17]
	v_pk_mul_f32 v[38:39], v[76:77], v[36:37] op_sel_hi:[0,1]
	v_pk_mul_f32 v[36:37], v[76:77], v[104:105] op_sel_hi:[0,1]
	v_pk_mul_f32 v[42:43], v[82:83], v[40:41] op_sel_hi:[0,1]
	v_pk_mul_f32 v[40:41], v[82:83], v[114:115] op_sel_hi:[0,1]
	v_pk_fma_f32 v[36:37], v[110:111], v[36:37], v[140:141]
	v_pk_fma_f32 v[38:39], v[112:113], v[38:39], v[142:143]
	v_pk_fma_f32 v[40:41], v[110:111], v[40:41], v[100:101]
	v_pk_fma_f32 v[42:43], v[112:113], v[42:43], v[102:103]
	global_store_dwordx4 v[128:129], v[12:15], off offset:1024 sc0 sc1 nt
	global_store_dwordx4 v[122:123], v[16:19], off offset:1024 sc0 sc1 nt
	global_store_dwordx4 v[118:119], v[36:39], off offset:1024 sc0 sc1 nt
	global_store_dwordx4 v[120:121], v[40:43], off offset:1024 sc0 sc1 nt
	s_nop 1
	v_mov_b32_e32 v100, v164
	v_mov_b32_e32 v101, v165
	v_mov_b32_e32 v102, v166
	v_mov_b32_e32 v103, v167
	v_pk_fma_f32 v[4:5], v[48:49], v[100:101], v[4:5]
	v_pk_fma_f32 v[6:7], v[50:51], v[102:103], v[6:7]
	v_pk_mul_f32 v[48:49], v[58:59], v[92:93] op_sel_hi:[0,1]
	v_pk_mul_f32 v[50:51], v[58:59], v[90:91] op_sel_hi:[0,1]
	v_pk_fma_f32 v[8:9], v[50:51], v[100:101], v[8:9]
	v_pk_fma_f32 v[10:11], v[48:49], v[102:103], v[10:11]
	v_pk_mul_f32 v[48:49], v[76:77], v[98:99] op_sel_hi:[0,1]
	v_pk_mul_f32 v[50:51], v[76:77], v[96:97] op_sel_hi:[0,1]
	v_pk_fma_f32 v[44:45], v[50:51], v[100:101], v[44:45]
	v_pk_fma_f32 v[46:47], v[48:49], v[102:103], v[46:47]
	v_pk_mul_f32 v[50:51], v[82:83], v[126:127] op_sel_hi:[0,1]
	v_pk_mul_f32 v[48:49], v[82:83], v[108:109] op_sel_hi:[0,1]
	v_pk_fma_f32 v[48:49], v[100:101], v[48:49], v[144:145]
	v_pk_fma_f32 v[50:51], v[102:103], v[50:51], v[146:147]
	global_store_dwordx4 v[128:129], v[4:7], off offset:2048 sc0 sc1 nt
	global_store_dwordx4 v[122:123], v[8:11], off offset:2048 sc0 sc1 nt
	global_store_dwordx4 v[118:119], v[44:47], off offset:2048 sc0 sc1 nt
	global_store_dwordx4 v[120:121], v[48:51], off offset:2048 sc0 sc1 nt
	s_nop 1
	v_mov_b32_e32 v90, v168
	v_mov_b32_e32 v91, v169
	v_mov_b32_e32 v92, v170
	v_mov_b32_e32 v93, v171
	v_pk_fma_f32 v[60:61], v[62:63], v[90:91], v[0:1]
	v_pk_mul_f32 v[0:1], v[58:59], v[56:57] op_sel_hi:[0,1]
	v_pk_fma_f32 v[62:63], v[86:87], v[92:93], v[2:3]
	v_pk_fma_f32 v[56:57], v[0:1], v[90:91], v[52:53]
	v_pk_mul_f32 v[0:1], v[76:77], v[78:79] op_sel_hi:[0,1]
	v_pk_mul_f32 v[2:3], v[76:77], v[74:75] op_sel_hi:[0,1]
	v_pk_fma_f32 v[58:59], v[88:89], v[92:93], v[54:55]
	v_pk_fma_f32 v[52:53], v[2:3], v[90:91], v[64:65]
	v_pk_fma_f32 v[54:55], v[0:1], v[92:93], v[66:67]
	v_pk_mul_f32 v[2:3], v[82:83], v[84:85] op_sel_hi:[0,1]
	v_pk_mul_f32 v[0:1], v[82:83], v[80:81] op_sel_hi:[0,1]
	v_pk_fma_f32 v[0:1], v[0:1], v[90:91], v[148:149]
	v_pk_fma_f32 v[2:3], v[2:3], v[92:93], v[150:151]
	global_store_dwordx4 v[128:129], v[60:63], off offset:3072 sc0 sc1 nt
	global_store_dwordx4 v[122:123], v[56:59], off offset:3072 sc0 sc1 nt
	global_store_dwordx4 v[118:119], v[52:55], off offset:3072 sc0 sc1 nt
	global_store_dwordx4 v[120:121], v[0:3], off offset:3072 sc0 sc1 nt
	s_cbranch_vccnz .LBB0_208
; __device__ __forceinline__ void ew_post(const bf16* Y, const float* xin, float* xout, const float* gpost, const float* gnext, bf16* H, int gw, int ngw, int lane) {
;     ...
;                 s2[q] += (xv[q][j].x * xv[q][j].x + xv[q][j].y * xv[q][j].y) + (xv[q][j].z * xv[q][j].z + xv[q][j].w * xv[q][j].w); } }
;         if (gnext) {
;             float r2[EW_NR];
; #pragma unroll
;             for (int q = 0; q < EW_NR; ++q) r2[q] = rsqrtf(wave_sum(s2[q]) * (1.f / DM) + RMS_EPS);
	v_pk_mul_f32 v[64:65], v[30:31], v[30:31]
	v_pk_mul_f32 v[66:67], v[28:29], v[28:29]
	v_mul_f32_e32 v78, v1, v1
	v_pk_mov_b32 v[74:75], v[66:67], v[64:65] op_sel:[1,0]
	v_mov_b32_e32 v67, v65
	v_pk_add_f32 v[64:65], v[74:75], v[66:67]
	v_pk_mul_f32 v[66:67], v[42:43], v[42:43]
	v_pk_mul_f32 v[74:75], v[40:41], v[40:41]
	v_mul_f32_e32 v79, v2, v2
	v_pk_mov_b32 v[76:77], v[74:75], v[66:67] op_sel:[1,0]
	v_mov_b32_e32 v75, v67
	v_pk_add_f32 v[66:67], v[76:77], v[74:75]
	v_mul_f32_e32 v74, v49, v49
	v_mul_f32_e32 v76, v0, v0
	v_pk_fma_f32 v[74:75], v[48:49], v[48:49], v[74:75] op_sel_hi:[1,1,0]
	v_mul_f32_e32 v80, v3, v3
	v_mov_b32_e32 v75, v76
	v_mul_f32_e32 v76, v51, v51
	v_pk_fma_f32 v[76:77], v[50:51], v[50:51], v[76:77] op_sel_hi:[1,1,0]
	v_pk_add_f32 v[64:65], v[64:65], v[64:65] op_sel:[0,1] op_sel_hi:[1,0]
	v_pk_add_f32 v[66:67], v[66:67], v[66:67] op_sel:[0,1] op_sel_hi:[1,0]
	v_mov_b32_e32 v77, v78
	v_mov_b32_e32 v65, v79
	v_mov_b32_e32 v67, v80
	v_pk_add_f32 v[74:75], v[74:75], v[76:77]
	v_pk_add_f32 v[64:65], v[64:65], v[66:67]
	v_pk_mul_f32 v[66:67], v[34:35], v[34:35]
	v_pk_add_f32 v[64:65], v[74:75], v[64:65]
	v_pk_mul_f32 v[74:75], v[32:33], v[32:33]
	v_mul_f32_e32 v86, v53, v53
	v_pk_mov_b32 v[76:77], v[74:75], v[66:67] op_sel:[1,0]
	v_mov_b32_e32 v75, v67
	v_pk_add_f32 v[66:67], v[76:77], v[74:75]
	v_pk_mul_f32 v[74:75], v[38:39], v[38:39]
	v_pk_mul_f32 v[76:77], v[36:37], v[36:37]
	v_pk_add_f32 v[66:67], v[66:67], v[66:67] op_sel:[0,1] op_sel_hi:[1,0]
	v_pk_mov_b32 v[78:79], v[76:77], v[74:75] op_sel:[1,0]
	v_mov_b32_e32 v77, v75
	v_pk_add_f32 v[74:75], v[78:79], v[76:77]
	v_mul_f32_e32 v76, v52, v52
	v_mov_b32_e32 v67, v76
	v_pk_mul_f32 v[76:77], v[26:27], v[26:27]
	v_pk_mul_f32 v[78:79], v[24:25], v[24:25]
	v_mul_f32_e32 v87, v54, v54
	v_pk_mov_b32 v[80:81], v[78:79], v[76:77] op_sel:[1,0]
	v_mov_b32_e32 v79, v77
	v_pk_add_f32 v[76:77], v[80:81], v[78:79]
	v_pk_mul_f32 v[78:79], v[18:19], v[18:19]
	v_pk_mul_f32 v[80:81], v[16:17], v[16:17]
	v_pk_add_f32 v[76:77], v[76:77], v[76:77] op_sel:[0,1] op_sel_hi:[1,0]
	v_pk_mov_b32 v[82:83], v[80:81], v[78:79] op_sel:[1,0]
	v_mov_b32_e32 v81, v79
	v_pk_add_f32 v[78:79], v[82:83], v[80:81]
	v_mul_f32_e32 v80, v56, v56
	v_mul_f32_e32 v81, v57, v57
	v_pk_add_f32 v[78:79], v[78:79], v[78:79] op_sel:[0,1] op_sel_hi:[1,0]
	v_mov_b32_e32 v77, v80
	v_mov_b32_e32 v79, v81
	v_pk_add_f32 v[76:77], v[76:77], v[78:79]
	v_mul_f32_e32 v78, v9, v9
	v_mul_f32_e32 v80, v11, v11
	v_mul_f32_e32 v82, v58, v58
	v_mul_f32_e32 v83, v59, v59
	v_pk_fma_f32 v[78:79], v[8:9], v[8:9], v[78:79] op_sel_hi:[1,1,0]
	v_pk_fma_f32 v[80:81], v[10:11], v[10:11], v[80:81] op_sel_hi:[1,1,0]
	v_mov_b32_e32 v79, v82
	v_mov_b32_e32 v81, v83
	v_pk_add_f32 v[78:79], v[78:79], v[80:81]
	v_pk_mul_f32 v[80:81], v[20:21], v[20:21]
	v_pk_add_f32 v[76:77], v[76:77], v[78:79]
	v_pk_mul_f32 v[78:79], v[22:23], v[22:23]
	v_mul_f32_e32 v88, v55, v55
	v_pk_mov_b32 v[82:83], v[80:81], v[78:79] op_sel:[1,0]
	v_mov_b32_e32 v81, v79
	v_pk_add_f32 v[78:79], v[82:83], v[80:81]
	v_pk_mul_f32 v[80:81], v[14:15], v[14:15]
	v_pk_mul_f32 v[82:83], v[12:13], v[12:13]
	v_pk_add_f32 v[78:79], v[78:79], v[78:79] op_sel:[0,1] op_sel_hi:[1,0]
	v_pk_mov_b32 v[84:85], v[82:83], v[80:81] op_sel:[1,0]
	v_mov_b32_e32 v83, v81
	v_pk_add_f32 v[80:81], v[84:85], v[82:83]
	v_mul_f32_e32 v82, v60, v60
	v_mul_f32_e32 v83, v61, v61
	v_pk_add_f32 v[80:81], v[80:81], v[80:81] op_sel:[0,1] op_sel_hi:[1,0]
	v_mov_b32_e32 v79, v82
	v_mov_b32_e32 v81, v83
	v_pk_add_f32 v[78:79], v[78:79], v[80:81]
	v_mul_f32_e32 v80, v5, v5
	v_mul_f32_e32 v82, v7, v7
	v_mul_f32_e32 v84, v62, v62
	v_mul_f32_e32 v85, v63, v63
	v_pk_fma_f32 v[80:81], v[4:5], v[4:5], v[80:81] op_sel_hi:[1,1,0]
	v_pk_fma_f32 v[82:83], v[6:7], v[6:7], v[82:83] op_sel_hi:[1,1,0]
	v_mov_b32_e32 v81, v84
	v_mov_b32_e32 v83, v85
	v_pk_add_f32 v[80:81], v[80:81], v[82:83]
	v_pk_add_f32 v[82:83], v[74:75], v[74:75] op_sel:[0,1] op_sel_hi:[1,0]
	v_pk_add_f32 v[78:79], v[78:79], v[80:81]
	v_mov_b32_e32 v80, v76
	v_mov_b32_e32 v81, v78
	v_mov_b32_e32 v78, v77
	s_nop 1
	v_mov_b32_e32 v74, v232
	v_mov_b32_e32 v75, v233
	v_mov_b32_e32 v76, v234
	v_mov_b32_e32 v77, v235
	v_pk_add_f32 v[78:79], v[80:81], v[78:79]
	v_mov_b32_e32 v83, v86
	ds_bpermute_b32 v81, v130, v79
	ds_bpermute_b32 v80, v130, v78
	v_pk_add_f32 v[66:67], v[66:67], v[82:83]
	v_mul_f32_e32 v82, v45, v45
	v_mul_f32_e32 v84, v47, v47
	v_pk_fma_f32 v[82:83], v[44:45], v[44:45], v[82:83] op_sel_hi:[1,1,0]
	v_pk_fma_f32 v[84:85], v[46:47], v[46:47], v[84:85] op_sel_hi:[1,1,0]
	v_mov_b32_e32 v83, v87
	v_mov_b32_e32 v85, v88
	v_pk_add_f32 v[82:83], v[82:83], v[84:85]
	s_waitcnt lgkmcnt(0)
	v_pk_add_f32 v[78:79], v[78:79], v[80:81]
	v_pk_add_f32 v[66:67], v[66:67], v[82:83]
	v_mov_b32_e32 v82, v64
	v_mov_b32_e32 v83, v66
	v_mov_b32_e32 v66, v65
	ds_bpermute_b32 v81, v131, v79
	ds_bpermute_b32 v80, v131, v78
	v_pk_add_f32 v[64:65], v[82:83], v[66:67]
	ds_bpermute_b32 v67, v130, v65
	ds_bpermute_b32 v66, v130, v64
	s_waitcnt lgkmcnt(2)
	v_pk_add_f32 v[78:79], v[78:79], v[80:81]
	ds_bpermute_b32 v81, v132, v79
	ds_bpermute_b32 v80, v132, v78
	s_waitcnt lgkmcnt(2)
	v_pk_add_f32 v[64:65], v[64:65], v[66:67]
	ds_bpermute_b32 v67, v131, v65
	ds_bpermute_b32 v66, v131, v64
	s_waitcnt lgkmcnt(2)
	v_pk_add_f32 v[78:79], v[78:79], v[80:81]
	ds_bpermute_b32 v81, v133, v79
	ds_bpermute_b32 v80, v133, v78
	s_waitcnt lgkmcnt(2)
	v_pk_add_f32 v[64:65], v[64:65], v[66:67]
	ds_bpermute_b32 v67, v132, v65
	ds_bpermute_b32 v66, v132, v64
	s_waitcnt lgkmcnt(2)
	v_pk_add_f32 v[78:79], v[78:79], v[80:81]
	ds_bpermute_b32 v81, v134, v79
	ds_bpermute_b32 v80, v134, v78
	s_waitcnt lgkmcnt(2)
; __device__ __forceinline__ void ew_post(const bf16* Y, const float* xin, float* xout, const float* gpost, const float* gnext, bf16* H, int gw, int ngw, int lane) {
;     ...
;             for (int q = 0; q < EW_NR; ++q) r2[q] = rsqrtf(wave_sum(s2[q]) * (1.f / DM) + RMS_EPS);
	v_pk_add_f32 v[64:65], v[64:65], v[66:67]
	ds_bpermute_b32 v67, v133, v65
	ds_bpermute_b32 v66, v133, v64
	s_waitcnt lgkmcnt(2)
	v_pk_add_f32 v[78:79], v[78:79], v[80:81]
	ds_bpermute_b32 v81, v135, v79
	ds_bpermute_b32 v80, v135, v78
	s_waitcnt lgkmcnt(2)
	v_pk_add_f32 v[64:65], v[64:65], v[66:67]
	ds_bpermute_b32 v67, v134, v65
	ds_bpermute_b32 v66, v134, v64
	s_waitcnt lgkmcnt(2)
	v_pk_add_f32 v[78:79], v[78:79], v[80:81]
	v_mov_b64_e32 v[80:81], s[26:27]
	v_pk_fma_f32 v[78:79], v[78:79], s[44:45], v[80:81] op_sel_hi:[1,0,0]
	s_waitcnt lgkmcnt(0)
	v_pk_add_f32 v[64:65], v[64:65], v[66:67]
	v_mul_f32_e32 v82, 0x4b800000, v79
	v_cmp_gt_f32_e32 vcc, s3, v79
	ds_bpermute_b32 v67, v135, v65
	ds_bpermute_b32 v66, v135, v64
	v_cndmask_b32_e32 v79, v79, v82, vcc
	v_rsq_f32_e32 v79, v79
	v_mul_f32_e32 v82, 0x4b800000, v78
	v_cmp_gt_f32_e64 s[4:5], s3, v78
	s_waitcnt lgkmcnt(0)
; __device__ __forceinline__ unsigned pk2(float lo, float hi) { f32v2 v = {lo, hi}; bf16v2 r = __builtin_convertvector(v, bf16v2); return __builtin_bit_cast(unsigned, r); }
; __device__ __forceinline__ void ew_post(const bf16* Y, const float* xin, float* xout, const float* gpost, const float* gnext, bf16* H, int gw, int ngw, int lane) {
;     ...
;             for (int q = 0; q < EW_NR; ++q) r2[q] = rsqrtf(wave_sum(s2[q]) * (1.f / DM) + RMS_EPS);
; #pragma unroll
;             for (int j = 0; j < 4; ++j) { const f32x4 g = *((const f32x4*)gnext + lane + 64 * j);
; #pragma unroll
;                 for (int q = 0; q < EW_NR; ++q) { v2u w; w.x = pk2(xv[q][j].x * r2[q] * g.x, xv[q][j].y * r2[q] * g.y); w.y = pk2(xv[q][j].z * r2[q] * g.z, xv[q][j].w * r2[q] * g.w);
;                     *((v2u*)(H + (size_t)(m0 + q) * DM) + lane + 64 * j) = w; } }
	v_pk_add_f32 v[64:65], v[64:65], v[66:67]
	v_cndmask_b32_e64 v78, v78, v82, s[4:5]
	v_rsq_f32_e32 v82, v78
	v_mul_f32_e32 v78, 0x45800000, v79
	v_pk_fma_f32 v[64:65], v[64:65], s[44:45], v[80:81] op_sel_hi:[1,0,0]
	v_cndmask_b32_e32 v78, v79, v78, vcc
	v_mul_f32_e32 v66, 0x4b800000, v65
	v_cmp_gt_f32_e32 vcc, s3, v65
	v_mul_f32_e32 v79, 0x45800000, v82
	v_cmp_gt_f32_e64 s[6:7], s3, v64
	v_cndmask_b32_e32 v65, v65, v66, vcc
	v_rsq_f32_e32 v65, v65
	v_mul_f32_e32 v66, 0x4b800000, v64
	v_pk_mul_f32 v[20:21], v[20:21], v[78:79] op_sel_hi:[1,0]
	v_pk_mul_f32 v[22:23], v[22:23], v[78:79] op_sel_hi:[1,0]
	v_mul_f32_e32 v67, 0x45800000, v65
	v_cndmask_b32_e64 v64, v64, v66, s[6:7]
	v_cndmask_b32_e64 v66, v82, v79, s[4:5]
	v_cndmask_b32_e32 v80, v65, v67, vcc
	v_pk_mul_f32 v[20:21], v[20:21], v[74:75]
	v_pk_mul_f32 v[22:23], v[22:23], v[76:77]
	v_add_co_u32_e32 v82, vcc, s20, v72
	v_cvt_pk_bf16_f32 v20, v20, v21
	v_cvt_pk_bf16_f32 v21, v22, v23
	v_addc_co_u32_e32 v83, vcc, -1, v73, vcc
	v_rsq_f32_e32 v64, v64
	global_store_dwordx2 v[82:83], v[20:21], off offset:-3584 sc0 sc1
	v_pk_mul_f32 v[20:21], v[24:25], v[66:67] op_sel_hi:[1,0]
	v_pk_mul_f32 v[22:23], v[26:27], v[66:67] op_sel_hi:[1,0]
	v_pk_mul_f32 v[20:21], v[20:21], v[74:75]
	v_pk_mul_f32 v[22:23], v[22:23], v[76:77]
	v_cvt_pk_bf16_f32 v20, v20, v21
	v_cvt_pk_bf16_f32 v21, v22, v23
	global_store_dwordx2 v[82:83], v[20:21], off offset:-1536 sc0 sc1
	v_pk_mul_f32 v[20:21], v[32:33], v[80:81] op_sel_hi:[1,0]
	v_pk_mul_f32 v[22:23], v[34:35], v[80:81] op_sel_hi:[1,0]
	v_mul_f32_e32 v65, 0x45800000, v64
	v_pk_mul_f32 v[20:21], v[74:75], v[20:21]
	v_pk_mul_f32 v[22:23], v[76:77], v[22:23]
	v_add_co_u32_e32 v24, vcc, s21, v72
	v_cndmask_b32_e64 v64, v64, v65, s[6:7]
	v_cvt_pk_bf16_f32 v20, v20, v21
	v_cvt_pk_bf16_f32 v21, v22, v23
	v_addc_co_u32_e32 v25, vcc, -1, v73, vcc
	global_store_dwordx2 v[24:25], v[20:21], off offset:-3584 sc0 sc1
	v_pk_mul_f32 v[20:21], v[28:29], v[64:65] op_sel_hi:[1,0]
	v_pk_mul_f32 v[22:23], v[30:31], v[64:65] op_sel_hi:[1,0]
	v_pk_mul_f32 v[20:21], v[74:75], v[20:21]
	v_pk_mul_f32 v[22:23], v[76:77], v[22:23]
	v_cvt_pk_bf16_f32 v20, v20, v21
	v_cvt_pk_bf16_f32 v21, v22, v23
	global_store_dwordx2 v[24:25], v[20:21], off offset:-1536 sc0 sc1
	s_nop 1
	v_mov_b32_e32 v20, v236
	v_mov_b32_e32 v21, v237
	v_mov_b32_e32 v22, v238
	v_mov_b32_e32 v23, v239
	v_pk_mul_f32 v[12:13], v[12:13], v[78:79] op_sel_hi:[1,0]
	v_pk_mul_f32 v[14:15], v[14:15], v[78:79] op_sel_hi:[1,0]
	v_pk_mul_f32 v[4:5], v[4:5], v[78:79] op_sel_hi:[1,0]
	v_pk_mul_f32 v[6:7], v[6:7], v[78:79] op_sel_hi:[1,0]
	v_pk_mul_f32 v[0:1], v[0:1], v[64:65] op_sel_hi:[1,0]
	v_pk_mul_f32 v[2:3], v[2:3], v[64:65] op_sel_hi:[1,0]
	v_pk_mul_f32 v[12:13], v[12:13], v[20:21]
	v_pk_mul_f32 v[14:15], v[14:15], v[22:23]
	v_cvt_pk_bf16_f32 v12, v12, v13
	v_cvt_pk_bf16_f32 v13, v14, v15
	global_store_dwordx2 v[82:83], v[12:13], off offset:-3072 sc0 sc1
	v_pk_mul_f32 v[12:13], v[16:17], v[66:67] op_sel_hi:[1,0]
	v_pk_mul_f32 v[14:15], v[18:19], v[66:67] op_sel_hi:[1,0]
	v_pk_mul_f32 v[12:13], v[12:13], v[20:21]
	v_pk_mul_f32 v[14:15], v[14:15], v[22:23]
	v_cvt_pk_bf16_f32 v12, v12, v13
	v_cvt_pk_bf16_f32 v13, v14, v15
	global_store_dwordx2 v[82:83], v[12:13], off offset:-1024 sc0 sc1
	v_pk_mul_f32 v[12:13], v[36:37], v[80:81] op_sel_hi:[1,0]
	v_pk_mul_f32 v[14:15], v[38:39], v[80:81] op_sel_hi:[1,0]
	v_pk_mul_f32 v[12:13], v[12:13], v[20:21]
	v_pk_mul_f32 v[14:15], v[14:15], v[22:23]
	v_cvt_pk_bf16_f32 v12, v12, v13
	v_cvt_pk_bf16_f32 v13, v14, v15
	global_store_dwordx2 v[24:25], v[12:13], off offset:-3072 sc0 sc1
	v_pk_mul_f32 v[12:13], v[40:41], v[64:65] op_sel_hi:[1,0]
	v_pk_mul_f32 v[14:15], v[42:43], v[64:65] op_sel_hi:[1,0]
	v_pk_mul_f32 v[12:13], v[20:21], v[12:13]
	v_pk_mul_f32 v[14:15], v[22:23], v[14:15]
	v_cvt_pk_bf16_f32 v12, v12, v13
	v_cvt_pk_bf16_f32 v13, v14, v15
	global_store_dwordx2 v[24:25], v[12:13], off offset:-1024 sc0 sc1
	s_nop 1
	v_mov_b32_e32 v12, v240
	v_mov_b32_e32 v13, v241
	v_mov_b32_e32 v14, v242
	v_mov_b32_e32 v15, v243
	v_pk_mul_f32 v[16:17], v[52:53], v[80:81] op_sel_hi:[1,0]
	v_pk_mul_f32 v[18:19], v[54:55], v[80:81] op_sel_hi:[1,0]
	v_pk_mul_f32 v[4:5], v[4:5], v[12:13]
	v_pk_mul_f32 v[6:7], v[6:7], v[14:15]
	v_cvt_pk_bf16_f32 v4, v4, v5
	v_cvt_pk_bf16_f32 v5, v6, v7
	global_store_dwordx2 v[82:83], v[4:5], off offset:-2560 sc0 sc1
	v_pk_mul_f32 v[4:5], v[8:9], v[66:67] op_sel_hi:[1,0]
	v_pk_mul_f32 v[6:7], v[10:11], v[66:67] op_sel_hi:[1,0]
	v_pk_mul_f32 v[4:5], v[4:5], v[12:13]
	v_pk_mul_f32 v[6:7], v[6:7], v[14:15]
	v_cvt_pk_bf16_f32 v4, v4, v5
	v_cvt_pk_bf16_f32 v5, v6, v7
	global_store_dwordx2 v[82:83], v[4:5], off offset:-512 sc0 sc1
	v_pk_mul_f32 v[4:5], v[44:45], v[80:81] op_sel_hi:[1,0]
	v_pk_mul_f32 v[6:7], v[46:47], v[80:81] op_sel_hi:[1,0]
	v_pk_mul_f32 v[4:5], v[4:5], v[12:13]
	v_pk_mul_f32 v[6:7], v[6:7], v[14:15]
	v_cvt_pk_bf16_f32 v4, v4, v5
	v_cvt_pk_bf16_f32 v5, v6, v7
	global_store_dwordx2 v[24:25], v[4:5], off offset:-2560 sc0 sc1
	v_pk_mul_f32 v[4:5], v[48:49], v[64:65] op_sel_hi:[1,0]
	v_pk_mul_f32 v[6:7], v[50:51], v[64:65] op_sel_hi:[1,0]
	v_pk_mul_f32 v[4:5], v[4:5], v[12:13]
	v_pk_mul_f32 v[6:7], v[6:7], v[14:15]
	v_cvt_pk_bf16_f32 v4, v4, v5
	v_cvt_pk_bf16_f32 v5, v6, v7
	global_store_dwordx2 v[24:25], v[4:5], off offset:-512 sc0 sc1
	s_nop 1
	v_mov_b32_e32 v4, v244
	v_mov_b32_e32 v5, v245
	v_mov_b32_e32 v6, v246
	v_mov_b32_e32 v7, v247
	v_pk_mul_f32 v[8:9], v[60:61], v[78:79] op_sel_hi:[1,0]
	v_pk_mul_f32 v[10:11], v[62:63], v[78:79] op_sel_hi:[1,0]
	v_pk_mul_f32 v[12:13], v[56:57], v[66:67] op_sel_hi:[1,0]
	v_pk_mul_f32 v[14:15], v[58:59], v[66:67] op_sel_hi:[1,0]
	v_pk_mul_f32 v[8:9], v[8:9], v[4:5]
	v_pk_mul_f32 v[10:11], v[10:11], v[6:7]
	v_pk_mul_f32 v[12:13], v[12:13], v[4:5]
	v_pk_mul_f32 v[14:15], v[14:15], v[6:7]
	v_pk_mul_f32 v[16:17], v[16:17], v[4:5]
	v_pk_mul_f32 v[18:19], v[18:19], v[6:7]
	v_pk_mul_f32 v[0:1], v[0:1], v[4:5]
	v_pk_mul_f32 v[2:3], v[2:3], v[6:7]
	v_cvt_pk_bf16_f32 v4, v8, v9
	v_cvt_pk_bf16_f32 v5, v10, v11
	v_cvt_pk_bf16_f32 v6, v12, v13
	v_cvt_pk_bf16_f32 v7, v14, v15
	v_cvt_pk_bf16_f32 v8, v16, v17
	v_cvt_pk_bf16_f32 v9, v18, v19
	v_cvt_pk_bf16_f32 v0, v0, v1
	v_cvt_pk_bf16_f32 v1, v2, v3
	global_store_dwordx2 v[82:83], v[4:5], off offset:-2048 sc0 sc1
	global_store_dwordx2 v[24:25], v[6:7], off offset:-4096 sc0 sc1
	global_store_dwordx2 v[24:25], v[8:9], off offset:-2048 sc0 sc1
	global_store_dwordx2 v[24:25], v[0:1], off sc0 sc1
	s_branch .LBB0_208
